# P5b epilogue rewritten: step-1 g/x1 loads as 4-group ring with counted vmcnt, g_final fetched once, step-5 store-only; P4 epilogue loads issued for all lanes (clamped rows)
# speedup vs baseline: 1.0298x; 1.0027x over previous
.LBB0_537:
	s_or_b64 exec, exec, s[0:1]
	s_and_b64 s[0:1], s[36:37], exec
	s_cselect_b32 s28, 16, 0x1000
	s_add_u32 s64, s76, 0x13d00000
	s_addc_u32 s65, s77, 0
	s_bfe_u32 s68, s96, 0x20006
	s_mul_i32 s0, s68, 0x3700
	s_add_i32 s71, s0, 0
	s_and_b32 s0, s96, 0xffffff00
	s_lshr_b32 s74, s96, 8
	s_add_i32 s84, s0, 0
	s_lshl_b32 s11, s74, 5
	s_add_i32 s80, s84, 0x12600
	s_cmpk_lt_u32 s96, 0x540
	v_readlane_b32 s20, v255, 31
	s_cselect_b64 s[40:41], -1, 0
	s_add_i32 s12, s20, -4
	s_lshl_b32 s13, s12, 2
	s_lshl_b32 s22, s12, 10
	s_cmpk_lt_u32 s96, 0x440
	s_cselect_b64 s[42:43], -1, 0
	s_lshl_b32 s66, s20, 10
	s_cmpk_lt_u32 s96, 0x340
	s_cselect_b64 s[46:47], -1, 0
	s_add_i32 s14, s20, 4
	s_lshl_b32 s15, s14, 2
	s_lshl_b32 s23, s14, 10
	s_cmpk_lt_u32 s96, 0x240
	s_cselect_b64 s[48:49], -1, 0
	s_add_i32 s16, s20, 8
	s_lshl_b32 s17, s16, 2
	s_lshl_b32 s24, s16, 10
	s_cmp_eq_u32 s20, 4
	s_cselect_b64 s[50:51], -1, 0
	s_cmp_eq_u32 s20, 2
	s_mov_b32 s0, 0xfc00000
	s_cselect_b32 s38, s0, 0x13d00000
	s_add_u32 s8, s76, s6
	s_addc_u32 s9, s77, 0
	s_mul_i32 s0, s20, 0x2400
	s_add_i32 s1, 0, 0x1a900
	s_add_i32 s81, s1, s0
	s_lshl_b32 s0, s74, 7
	s_add_i32 s83, s0, 0
	s_add_i32 s82, s81, 0x2000
	s_add_i32 s83, s83, 0x14800
	s_add_i32 s84, s84, 0x12400
	s_lshl_b32 s29, s20, 5
	s_add_u32 s6, s64, s6
	s_addc_u32 s7, s65, 0
	s_lshl_b32 s85, s33, 10
	s_add_u32 s18, s76, 0x10000
	v_writelane_b32 v255, s96, 33
	s_addc_u32 s19, s77, 0
	v_lshl_or_b32 v11, s68, 4, v9
	v_writelane_b32 v255, s18, 34
	v_add_u32_e32 v25, 1, v11
	v_lshlrev_b32_e32 v27, 3, v38
	v_writelane_b32 v255, s19, 35
	v_lshlrev_b32_e32 v10, 7, v25
	v_and_b32_e32 v22, 8, v27
	s_add_i32 s0, 0, 0x1cd00
	s_add_i32 s18, 0, 0x1f100
	v_add3_u32 v91, s1, v10, v22
	v_add3_u32 v92, s0, v10, v22
	v_add3_u32 v93, s18, v10, v22
	v_lshlrev_b32_e32 v10, 8, v25
	s_add_i32 s19, 0, 0x23900
	v_add3_u32 v28, s19, v10, v22
	v_lshlrev_b32_e32 v10, 7, v11
	v_add3_u32 v94, s1, v10, v22
	v_add3_u32 v95, s0, v10, v22
	v_add3_u32 v96, s18, v10, v22
	v_lshlrev_b32_e32 v10, 8, v11
	v_add3_u32 v29, s19, v10, v22
	v_add_u32_e32 v10, 1, v89
	s_add_i32 s19, 0, 0x21500
	v_lshl_add_u32 v32, v10, 7, s19
	v_xor_b32_e32 v10, v10, v39
	v_lshlrev_b32_e32 v10, 4, v10
	v_and_b32_e32 v33, 0x70, v10
	v_lshlrev_b32_e32 v10, 7, v89
	v_add_u32_e32 v34, s19, v10
	s_add_i32 s19, 0, 0x12800
	s_cmp_lg_u32 s12, 16
	v_add_u32_e32 v36, s19, v10
	v_or_b32_e32 v10, s13, v38
	s_cselect_b64 vcc, -1, 0
	v_xor_b32_e32 v22, v89, v39
	v_cndmask_b32_e32 v98, 64, v10, vcc
	v_bitop3_b32 v10, v38, v39, s13 bitop3:0x36
	v_lshlrev_b32_e32 v22, 4, v22
	v_and_or_b32 v10, v10, 7, v41
	v_and_b32_e32 v35, 0x70, v22
	v_lshlrev_b32_e32 v22, 4, v10
	v_mov_b32_e32 v10, 0
	v_mov_b32_e32 v23, v10
	s_cmp_lg_u32 s20, 16
	v_lshl_add_u64 v[48:49], s[4:5], 0, v[22:23]
	v_or_b32_e32 v22, s3, v38
	s_cselect_b64 vcc, -1, 0
	v_cndmask_b32_e32 v99, 64, v22, vcc
	v_bitop3_b32 v22, v38, v39, s3 bitop3:0x36
	v_and_or_b32 v22, v22, 7, v41
	v_lshlrev_b32_e32 v22, 4, v22
	s_cmp_lg_u32 s14, 16
	v_lshl_add_u64 v[50:51], s[4:5], 0, v[22:23]
	v_or_b32_e32 v22, s15, v38
	s_cselect_b64 vcc, -1, 0
	v_cndmask_b32_e32 v100, 64, v22, vcc
	v_bitop3_b32 v22, v38, v39, s15 bitop3:0x36
	v_and_or_b32 v22, v22, 7, v41
	v_lshlrev_b32_e32 v22, 4, v22
	s_cmp_lg_u32 s16, 16
	v_lshl_add_u64 v[52:53], s[4:5], 0, v[22:23]
	v_or_b32_e32 v22, s17, v38
	s_cselect_b64 vcc, -1, 0
	v_cndmask_b32_e32 v101, 64, v22, vcc
	v_bitop3_b32 v22, v38, v39, s17 bitop3:0x36
	v_and_or_b32 v22, v22, 7, v41
	v_lshlrev_b32_e32 v22, 4, v22
	v_lshl_add_u64 v[54:55], s[4:5], 0, v[22:23]
	v_xor_b32_e32 v22, v38, v20
	s_movk_i32 s10, 0x3700
	v_or_b32_e32 v22, v22, v41
	v_lshlrev_b32_e32 v41, 5, v9
	v_lshrrev_b32_e32 v45, 7, v42
	v_cmp_gt_u32_e64 s[0:1], 16, v40
	v_or_b32_e32 v103, v27, v41
	v_lshl_add_u32 v104, v40, 2, s71
	v_add_u32_e32 v40, s71, v41
	v_lshrrev_b32_e32 v41, 2, v9
	v_mul_lo_u32 v45, v45, s10
	v_or_b32_e32 v41, v90, v41
	v_add_u32_e32 v67, 0, v45
	v_bfe_u32 v45, v42, 3, 4
	v_mul_u32_u24_e32 v41, 0x48, v41
	v_and_b32_e32 v21, 12, v21
	v_mul_u32_u24_e32 v45, 0x48, v45
	v_or_b32_e32 v24, s11, v90
	v_add_lshl_u32 v105, v21, v41, 1
	v_lshl_or_b32 v21, v89, 6, v8
	v_add_lshl_u32 v8, v45, v8, 1
	v_mov_b32_e32 v45, v10
	v_and_b32_e32 v26, 7, v25
	v_lshl_add_u64 v[60:61], s[6:7], 0, v[44:45]
	v_cmp_eq_u32_e64 s[6:7], 0, v42
	v_lshrrev_b32_e32 v42, 3, v24
	v_and_b32_e32 v62, 8, v42
	v_bitop3_b32 v63, v42, v26, 5 bitop3:0x6c
	v_or_b32_e32 v63, v63, v62
	v_lshlrev_b32_e32 v68, 4, v63
	v_add_u32_e32 v63, 64, v24
	v_bitop3_b32 v45, v42, v25, 7 bitop3:0x78
	v_lshrrev_b32_e32 v64, 3, v63
	v_xor_b32_e32 v69, v42, v20
	v_bitop3_b32 v42, v42, v20, 5 bitop3:0x6c
	v_and_b32_e32 v65, 8, v64
	v_or_b32_e32 v42, v42, v62
	v_bitop3_b32 v62, v64, v20, 5 bitop3:0x6c
	v_or_b32_e32 v62, v62, v65
	v_lshlrev_b32_e32 v108, 4, v69
	v_lshlrev_b32_e32 v69, 4, v62
	v_or_b32_e32 v62, 16, v24
	v_lshlrev_b32_e32 v22, 4, v22
	v_lshlrev_b32_e32 v71, 1, v63
	v_lshrrev_b32_e32 v63, 3, v62
	v_lshl_add_u64 v[56:57], s[4:5], 0, v[22:23]
	v_xor_b32_e32 v22, v88, v20
	v_bitop3_b32 v26, v64, v26, 5 bitop3:0x6c
	v_bitop3_b32 v64, v63, v25, 7 bitop3:0x78
	v_lshlrev_b32_e32 v22, 4, v22
	v_or_b32_e32 v26, v26, v65
	v_lshlrev_b32_e32 v111, 4, v64
	v_and_b32_e32 v64, 8, v63
	v_bitop3_b32 v65, v63, v25, 7 bitop3:0x28
	s_movk_i32 s18, 0x48
	v_lshl_add_u64 v[58:59], s[8:9], 0, v[22:23]
	v_or_b32_e32 v23, s11, v9
	v_or_b32_e32 v65, v65, v64
	v_mul_u32_u24_e32 v30, 0x48, v11
	v_mul_u32_u24_e32 v31, 0x48, v9
	v_lshlrev_b32_e32 v97, 2, v11
	v_or_b32_e32 v22, 16, v90
	v_lshlrev_b32_e32 v72, 4, v65
	v_add_u32_e32 v65, 0x50, v24
	v_mul_lo_u32 v23, v23, s18
	v_mad_u32_u24 v11, v11, s18, 32
	v_lshlrev_b32_e32 v70, 1, v24
	v_add_lshl_u32 v109, v24, v30, 1
	v_add_lshl_u32 v110, v24, v31, 1
	v_lshrrev_b32_e32 v73, 3, v65
	v_xor_b32_e32 v75, v63, v20
	v_bitop3_b32 v63, v63, v20, 7 bitop3:0x6c
	v_add_lshl_u32 v113, v62, v30, 1
	v_add_lshl_u32 v115, v30, v90, 1
	v_add_lshl_u32 v116, v22, v30, 1
	v_add_u32_e32 v30, 0x480, v23
	v_add_lshl_u32 v119, v11, v90, 1
	v_add_lshl_u32 v120, v11, v22, 1
	v_or_b32_e32 v11, 32, v90
	v_lshlrev_b32_e32 v123, 2, v24
	v_or_b32_e32 v24, 1, v90
	v_cmp_eq_u32_e32 vcc, v90, v9
	v_lshlrev_b32_e32 v106, 5, v20
	v_and_b32_e32 v74, 8, v73
	v_bitop3_b32 v25, v73, v25, 7 bitop3:0x28
	v_or_b32_e32 v63, v63, v64
	v_bitop3_b32 v20, v73, v20, 7 bitop3:0x6c
	v_lshlrev_b32_e32 v73, 1, v62
	v_add_lshl_u32 v114, v62, v31, 1
	v_add_lshl_u32 v118, v30, v90, 1
	v_add_lshl_u32 v122, v11, v30, 1
	v_lshlrev_b32_e32 v124, 2, v62
	v_or_b32_e32 v30, 2, v90
	v_cndmask_b32_e64 v62, 0, 1.0, vcc
	v_cmp_eq_u32_e32 vcc, v24, v9
	v_lshlrev_b32_e32 v112, 4, v75
	v_lshlrev_b32_e32 v75, 4, v63
	v_add_lshl_u32 v117, v90, v23, 1
	v_add_lshl_u32 v121, v11, v23, 1
	v_add_lshl_u32 v125, v90, v31, 1
	v_add_lshl_u32 v23, v11, v31, 1
	v_or_b32_e32 v31, 3, v90
	v_cndmask_b32_e64 v63, 0, 1.0, vcc
	v_cmp_eq_u32_e32 vcc, v30, v9
	v_cmp_eq_u32_e64 s[4:5], 0, v9
	v_mad_u32_u24 v37, v9, s18, 16
	v_cmp_lt_u32_e64 s[8:9], v90, v9
	v_cmp_gt_u32_e64 s[10:11], v90, v9
	v_cmp_lt_u32_e64 s[12:13], v24, v9
	v_cmp_lt_u32_e64 s[14:15], v30, v9
	v_cmp_gt_u32_e64 s[16:17], v30, v9
	v_cmp_lt_u32_e64 s[18:19], v31, v9
	v_cmp_gt_u32_e64 s[20:21], v31, v9
	v_cndmask_b32_e64 v64, 0, 1.0, vcc
	v_cmp_eq_u32_e32 vcc, v31, v9
	v_lshlrev_b32_e32 v9, 2, v9
	v_lshl_add_u32 v24, v38, 10, s97
	s_mov_b32 s3, 0xdc00
	v_add3_u32 v126, v24, v9, s3
	v_and_b32_e32 v9, 3, v39
	s_movk_i32 s25, 0x2400
	v_lshlrev_b32_e32 v43, 2, v21
	v_lshlrev_b32_e32 v21, 1, v21
	v_lshl_or_b32 v9, v9, 3, s29
	v_lshlrev_b32_e32 v24, 1, v41
	s_waitcnt lgkmcnt(0)
	s_barrier
	v_lshlrev_b32_e32 v66, 2, v89
	v_or_b32_e32 v25, v25, v74
	v_or_b32_e32 v20, v20, v74
	v_add3_u32 v128, v9, v24, s25
	v_mov_b32_e32 v9, 0x3540
	v_add_u32_e32 v151, v67, v8
	v_add_u32_e32 v8, 0, v21
	s_mov_b32 s39, 0
	v_and_b32_e32 v102, 48, v39
	v_lshlrev_b32_e32 v26, 4, v26
	v_lshlrev_b32_e32 v42, 4, v42
	v_lshlrev_b32_e32 v25, 4, v25
	v_lshlrev_b32_e32 v20, 4, v20
	v_lshlrev_b32_e32 v74, 1, v65
	v_add_lshl_u32 v22, v37, v90, 1
	v_add_lshl_u32 v11, v11, v37, 1
	v_writelane_b32 v255, s97, 32
	v_lshl_or_b32 v129, v38, 4, v9
	s_add_i32 s3, 0, 0x15c00
	s_add_i32 s88, s22, 0
	s_add_i32 s89, s23, 0
	s_add_i32 s90, s24, 0
	v_add_u32_e32 v9, 0, v66
	v_add_u32_e32 v152, 0x12800, v8
	v_mbcnt_lo_u32_b32 v8, -1, 0
	s_mov_b64 s[52:53], s[38:39]
	v_add_u32_e32 v107, s70, v89
	v_lshlrev_b32_e32 v45, 4, v45
	v_cndmask_b32_e64 v65, 0, 1.0, vcc
	v_add_u32_e32 v127, 0x2d00, v103
	v_writelane_b32 v255, s29, 44
	v_or_b32_e32 v130, 0x3500, v102
	v_add_u32_e32 v131, v28, v68
	v_add_u32_e32 v132, v28, v26
	v_add_u32_e32 v133, v29, v42
	v_add_u32_e32 v134, v29, v69
	v_add_u32_e32 v135, s3, v70
	v_add_u32_e32 v136, s3, v71
	s_mov_b32 s86, 0x4038aa3b
	s_add_i32 s67, 0, 0x10000
	v_add_u32_e32 v137, v28, v72
	v_add_u32_e32 v138, v28, v25
	v_add_u32_e32 v139, v29, v75
	v_add_u32_e32 v140, v29, v20
	v_add_u32_e32 v141, s3, v73
	v_add_u32_e32 v142, s3, v74
	v_add_u32_e32 v143, v32, v33
	v_add_u32_e32 v145, v34, v35
	s_mov_b32 s87, 0xbfb8aa3b
	v_add_u32_e32 v146, v36, v44
	s_add_i32 s88, s88, 0x23900
	s_add_i32 s89, s89, 0x23900
	s_add_i32 s90, s90, 0x23900
	s_add_i32 s91, 0, 0x27900
	s_add_i32 s92, s81, 0x400
	s_add_i32 s93, s81, 0x800
	s_add_i32 s94, s81, 0xc00
	s_add_i32 s95, s81, 0x1400
	s_add_i32 s96, s81, 0x1800
	s_add_i32 s97, s81, 0x1c00
	s_add_i32 s3, 0, 0x16100
	s_add_i32 s69, 0, 0x18500
	v_mov_b32_e32 v147, 0xbf92477c
	v_add_u32_e32 v148, v40, v27
	s_xor_b64 s[54:55], s[26:27], -1
	v_add_u32_e32 v149, 0, v43
	v_add_u32_e32 v150, 0x12400, v9
	v_mov_b32_e32 v153, 0x3a27c5ac
	v_mbcnt_hi_u32_b32 v144, -1, v8
	v_add_u32_e32 v154, s71, v22
	v_add_u32_e32 v155, s71, v23
	v_add_u32_e32 v156, s71, v11
	s_mov_b32 s33, s28
	s_mov_b32 s29, 0
	v_add_u32_e32 v207, v92, v45
	v_add_u32_e32 v234, s67, v120
	v_add_u32_e32 v213, s67, v109
	v_xor_b32_e32 v242, 16, v144
	v_and_b32_e32 v241, 64, v144
	v_add_u32_e32 v21, 64, v241
	v_cmp_lt_i32_e32 vcc, v242, v21
	s_nop 1
	v_cndmask_b32_e32 v20, v144, v242, vcc
	v_lshlrev_b32_e32 v221, 2, v20
	v_add_u32_e32 v229, s3, v117
	v_add_u32_e32 v233, s67, v119
	v_add_u32_e32 v236, s69, v121
	v_add_u32_e32 v232, s69, v118
	v_add_u32_e32 v224, s71, v114
	v_add_u32_e32 v209, v95, v108
	v_add_u32_e32 v216, v94, v112
	v_add_u32_e32 v237, s3, v122
	v_add_u32_e32 v239, 0x12600, v97
	v_add_u32_e32 v223, s67, v113
	v_add_u32_e32 v211, v93, v45
	v_add_u32_e32 v210, v96, v108
	v_add_u32_e32 v215, v92, v111
	v_xor_b32_e32 v243, 32, v144
	v_cmp_lt_i32_e32 vcc, v243, v21
	s_nop 1
	v_cndmask_b32_e32 v22, v144, v243, vcc
	v_lshlrev_b32_e32 v222, 2, v22
	v_add_u32_e32 v238, s69, v122
	v_or_b32_e32 v240, v102, v241
	v_add_u32_e32 v214, s71, v110
	v_add_u32_e32 v231, s3, v118
	v_add_u32_e32 v228, s67, v116
	v_add_u32_e32 v227, s67, v115
	v_add_u32_e32 v226, s83, v102
	v_add_u32_e32 v235, s3, v121
	v_add_u32_e32 v220, v91, v111
	v_add_u32_e32 v230, s69, v117
	v_add_u32_e32 v218, v96, v112
	v_add_u32_e32 v208, v94, v108
	v_add_u32_e32 v212, v91, v45
	v_add_u32_e32 v219, v93, v111
	v_add_u32_e32 v217, v95, v112
	v_add_u32_e32 v225, 0x15d80, v44
	s_waitcnt vmcnt(0)

.LBB0_1332:
	v_lshl_add_u32 v132, s18, 8, v146
	s_lshl_b32 s24, s34, 9
	s_or_b32 s24, s24, s57
	v_or_b32_e32 v133, s24, v145
	s_lshl_b32 s24, s34, 2
	s_or_b32 s26, s24, s52
	v_cmp_gt_i32_e64 s[0:1], s67, v132
	v_mov_b32_e32 v170, 0
	s_nop 0
	v_cndmask_b32_e64 v250, 0, v132, s[0:1]
	v_lshl_or_b32 v162, v250, 11, v133
	v_ashrrev_i32_e32 v251, 31, v250
	v_lshl_add_u64 v[250:251], v[250:251], 2, s[10:11]
	global_load_dword v154, v[250:251], off
	global_load_dwordx4 v[178:181], v162, s[6:7]
	global_load_dwordx4 v[182:185], v162, s[6:7] offset:256
	v_or_b32_e32 v128, 16, v132
	v_cmp_gt_i32_e64 s[0:1], s67, v128
	v_mov_b32_e32 v171, 0
	s_nop 0
	v_cndmask_b32_e64 v250, 0, v128, s[0:1]
	v_lshl_or_b32 v163, v250, 11, v133
	v_ashrrev_i32_e32 v251, 31, v250
	v_lshl_add_u64 v[250:251], v[250:251], 2, s[10:11]
	global_load_dword v155, v[250:251], off
	global_load_dwordx4 v[186:189], v163, s[6:7]
	global_load_dwordx4 v[190:193], v163, s[6:7] offset:256
	v_or_b32_e32 v128, 32, v132
	v_cmp_gt_i32_e64 s[0:1], s67, v128
	v_mov_b32_e32 v172, 0
	s_nop 0
	v_cndmask_b32_e64 v250, 0, v128, s[0:1]
	v_lshl_or_b32 v164, v250, 11, v133
	v_ashrrev_i32_e32 v251, 31, v250
	v_lshl_add_u64 v[250:251], v[250:251], 2, s[10:11]
	global_load_dword v156, v[250:251], off
	global_load_dwordx4 v[194:197], v164, s[6:7]
	global_load_dwordx4 v[198:201], v164, s[6:7] offset:256
	v_or_b32_e32 v128, 48, v132
	v_cmp_gt_i32_e64 s[0:1], s67, v128
	v_mov_b32_e32 v173, 0
	s_nop 0
	v_cndmask_b32_e64 v250, 0, v128, s[0:1]
	v_lshl_or_b32 v165, v250, 11, v133
	v_ashrrev_i32_e32 v251, 31, v250
	v_lshl_add_u64 v[250:251], v[250:251], 2, s[10:11]
	global_load_dword v157, v[250:251], off
	global_load_dwordx4 v[202:205], v165, s[6:7]
	global_load_dwordx4 v[206:209], v165, s[6:7] offset:256
	v_add_u32_e32 v128, 0x80, v132
	v_cmp_gt_i32_e64 s[0:1], s67, v128
	v_mov_b32_e32 v174, 0
	s_nop 0
	v_cndmask_b32_e64 v250, 0, v128, s[0:1]
	v_lshl_or_b32 v166, v250, 11, v133
	v_ashrrev_i32_e32 v251, 31, v250
	v_lshl_add_u64 v[250:251], v[250:251], 2, s[10:11]
	global_load_dword v158, v[250:251], off
	global_load_dwordx4 v[210:213], v166, s[6:7]
	global_load_dwordx4 v[214:217], v166, s[6:7] offset:256
	v_add_u32_e32 v128, 0x90, v132
	v_cmp_gt_i32_e64 s[0:1], s67, v128
	v_mov_b32_e32 v175, 0
	s_nop 0
	v_cndmask_b32_e64 v250, 0, v128, s[0:1]
	v_lshl_or_b32 v167, v250, 11, v133
	v_ashrrev_i32_e32 v251, 31, v250
	v_lshl_add_u64 v[250:251], v[250:251], 2, s[10:11]
	global_load_dword v159, v[250:251], off
	global_load_dwordx4 v[218:221], v167, s[6:7]
	global_load_dwordx4 v[222:225], v167, s[6:7] offset:256
	v_add_u32_e32 v128, 0xa0, v132
	v_cmp_gt_i32_e64 s[0:1], s67, v128
	v_mov_b32_e32 v176, 0
	s_nop 0
	v_cndmask_b32_e64 v250, 0, v128, s[0:1]
	v_lshl_or_b32 v168, v250, 11, v133
	v_ashrrev_i32_e32 v251, 31, v250
	v_lshl_add_u64 v[250:251], v[250:251], 2, s[10:11]
	global_load_dword v160, v[250:251], off
	global_load_dwordx4 v[226:229], v168, s[6:7]
	global_load_dwordx4 v[230:233], v168, s[6:7] offset:256
	v_add_u32_e32 v128, 0xb0, v132
	v_cmp_gt_i32_e64 s[0:1], s67, v128
	v_mov_b32_e32 v177, 0
	s_nop 0
	v_cndmask_b32_e64 v250, 0, v128, s[0:1]
	v_lshl_or_b32 v169, v250, 11, v133
	v_ashrrev_i32_e32 v251, 31, v250
	v_lshl_add_u64 v[250:251], v[250:251], 2, s[10:11]
	global_load_dword v161, v[250:251], off
	global_load_dwordx4 v[234:237], v169, s[6:7]
	global_load_dwordx4 v[238:241], v169, s[6:7] offset:256
	v_and_b32_e32 v137, 64, v142
	v_xor_b32_e32 v136, 16, v142
	v_add_u32_e32 v137, 64, v137
	v_xor_b32_e32 v138, 32, v142
	v_cmp_lt_i32_e32 vcc, v136, v137
	s_nop 1
	v_cndmask_b32_e32 v136, v142, v136, vcc
	v_lshlrev_b32_e32 v134, 2, v136
	v_cmp_lt_i32_e32 vcc, v138, v137
	s_nop 1
	v_cndmask_b32_e32 v137, v142, v138, vcc
	v_lshlrev_b32_e32 v135, 2, v137
	v_cmp_eq_u32_e32 vcc, 0, v144
	v_cmp_gt_i32_e64 s[0:1], s67, v132
	s_waitcnt vmcnt(23)
	v_mov_b32_e32 v130, v154
	v_mov_b32_e32 v131, v154
	s_and_saveexec_b64 s[24:25], s[0:1]
	s_waitcnt vmcnt(22)
	v_cvt_f32_f16_e32 v146, v178
	v_cvt_f32_f16_sdwa v147, v178 dst_sel:DWORD dst_unused:UNUSED_PAD src0_sel:WORD_1
	v_cvt_f32_f16_e32 v148, v179
	v_cvt_f32_f16_sdwa v149, v179 dst_sel:DWORD dst_unused:UNUSED_PAD src0_sel:WORD_1
	v_cvt_f32_f16_e32 v150, v180
	v_cvt_f32_f16_sdwa v151, v180 dst_sel:DWORD dst_unused:UNUSED_PAD src0_sel:WORD_1
	v_cvt_f32_f16_e32 v152, v181
	v_cvt_f32_f16_sdwa v153, v181 dst_sel:DWORD dst_unused:UNUSED_PAD src0_sel:WORD_1
	v_pk_fma_f32 v[124:125], v[130:131], v[146:147], v[124:125]
	v_pk_fma_f32 v[126:127], v[130:131], v[148:149], v[126:127]
	v_pk_fma_f32 v[120:121], v[130:131], v[150:151], v[120:121]
	v_pk_fma_f32 v[122:123], v[130:131], v[152:153], v[122:123]
	v_cvt_pk_f16_f32 v178, v124, v125
	v_cvt_pk_f16_f32 v179, v126, v127
	v_cvt_pk_f16_f32 v180, v120, v121
	v_cvt_pk_f16_f32 v181, v122, v123
	v_pk_mul_f32 v[124:125], v[124:125], v[124:125]
	v_pk_mul_f32 v[126:127], v[126:127], v[126:127]
	v_pk_mul_f32 v[120:121], v[120:121], v[120:121]
	v_pk_mul_f32 v[122:123], v[122:123], v[122:123]
	global_store_dwordx4 v162, v[178:181], s[8:9] sc1
	s_nop 1
	v_add_f32_e32 v136, v124, v125
	v_add_f32_e32 v137, v126, v127
	v_add_f32_e32 v138, v120, v121
	v_add_f32_e32 v139, v122, v123
	v_add_f32_e32 v136, v136, v137
	v_add_f32_e32 v136, v138, v136
	v_add_f32_e32 v170, v139, v136
	s_waitcnt vmcnt(22)
	v_cvt_f32_f16_e32 v146, v182
	v_cvt_f32_f16_sdwa v147, v182 dst_sel:DWORD dst_unused:UNUSED_PAD src0_sel:WORD_1
	v_cvt_f32_f16_e32 v148, v183
	v_cvt_f32_f16_sdwa v149, v183 dst_sel:DWORD dst_unused:UNUSED_PAD src0_sel:WORD_1
	v_cvt_f32_f16_e32 v150, v184
	v_cvt_f32_f16_sdwa v151, v184 dst_sel:DWORD dst_unused:UNUSED_PAD src0_sel:WORD_1
	v_cvt_f32_f16_e32 v152, v185
	v_cvt_f32_f16_sdwa v153, v185 dst_sel:DWORD dst_unused:UNUSED_PAD src0_sel:WORD_1
	v_pk_fma_f32 v[116:117], v[130:131], v[146:147], v[116:117]
	v_pk_fma_f32 v[118:119], v[130:131], v[148:149], v[118:119]
	v_pk_fma_f32 v[112:113], v[130:131], v[150:151], v[112:113]
	v_pk_fma_f32 v[114:115], v[130:131], v[152:153], v[114:115]
	v_cvt_pk_f16_f32 v182, v116, v117
	v_cvt_pk_f16_f32 v183, v118, v119
	v_cvt_pk_f16_f32 v184, v112, v113
	v_cvt_pk_f16_f32 v185, v114, v115
	v_pk_mul_f32 v[116:117], v[116:117], v[116:117]
	v_pk_mul_f32 v[118:119], v[118:119], v[118:119]
	v_pk_mul_f32 v[112:113], v[112:113], v[112:113]
	v_pk_mul_f32 v[114:115], v[114:115], v[114:115]
	global_store_dwordx4 v162, v[182:185], s[8:9] offset:256 sc1
	s_nop 1
	v_add_f32_e32 v136, v116, v117
	v_add_f32_e32 v137, v118, v119
	v_add_f32_e32 v138, v112, v113
	v_add_f32_e32 v139, v114, v115
	v_add_f32_e32 v136, v136, v137
	v_add_f32_e32 v136, v138, v136
	v_add_f32_e32 v136, v139, v136
	v_add_f32_e32 v170, v170, v136
	s_mov_b64 exec, s[24:25]
	v_or_b32_e32 v128, 16, v132
	v_cmp_gt_i32_e64 s[0:1], s67, v128
	s_waitcnt vmcnt(22)
	v_mov_b32_e32 v130, v155
	v_mov_b32_e32 v131, v155
	s_and_saveexec_b64 s[24:25], s[0:1]
	s_waitcnt vmcnt(21)
	v_cvt_f32_f16_e32 v146, v186
	v_cvt_f32_f16_sdwa v147, v186 dst_sel:DWORD dst_unused:UNUSED_PAD src0_sel:WORD_1
	v_cvt_f32_f16_e32 v148, v187
	v_cvt_f32_f16_sdwa v149, v187 dst_sel:DWORD dst_unused:UNUSED_PAD src0_sel:WORD_1
	v_cvt_f32_f16_e32 v150, v188
	v_cvt_f32_f16_sdwa v151, v188 dst_sel:DWORD dst_unused:UNUSED_PAD src0_sel:WORD_1
	v_cvt_f32_f16_e32 v152, v189
	v_cvt_f32_f16_sdwa v153, v189 dst_sel:DWORD dst_unused:UNUSED_PAD src0_sel:WORD_1
	v_pk_fma_f32 v[108:109], v[130:131], v[146:147], v[108:109]
	v_pk_fma_f32 v[110:111], v[130:131], v[148:149], v[110:111]
	v_pk_fma_f32 v[104:105], v[130:131], v[150:151], v[104:105]
	v_pk_fma_f32 v[106:107], v[130:131], v[152:153], v[106:107]
	v_cvt_pk_f16_f32 v186, v108, v109
	v_cvt_pk_f16_f32 v187, v110, v111
	v_cvt_pk_f16_f32 v188, v104, v105
	v_cvt_pk_f16_f32 v189, v106, v107
	v_pk_mul_f32 v[108:109], v[108:109], v[108:109]
	v_pk_mul_f32 v[110:111], v[110:111], v[110:111]
	v_pk_mul_f32 v[104:105], v[104:105], v[104:105]
	v_pk_mul_f32 v[106:107], v[106:107], v[106:107]
	global_store_dwordx4 v163, v[186:189], s[8:9] sc1
	s_nop 1
	v_add_f32_e32 v136, v108, v109
	v_add_f32_e32 v137, v110, v111
	v_add_f32_e32 v138, v104, v105
	v_add_f32_e32 v139, v106, v107
	v_add_f32_e32 v136, v136, v137
	v_add_f32_e32 v136, v138, v136
	v_add_f32_e32 v171, v139, v136
	s_waitcnt vmcnt(21)
	v_cvt_f32_f16_e32 v146, v190
	v_cvt_f32_f16_sdwa v147, v190 dst_sel:DWORD dst_unused:UNUSED_PAD src0_sel:WORD_1
	v_cvt_f32_f16_e32 v148, v191
	v_cvt_f32_f16_sdwa v149, v191 dst_sel:DWORD dst_unused:UNUSED_PAD src0_sel:WORD_1
	v_cvt_f32_f16_e32 v150, v192
	v_cvt_f32_f16_sdwa v151, v192 dst_sel:DWORD dst_unused:UNUSED_PAD src0_sel:WORD_1
	v_cvt_f32_f16_e32 v152, v193
	v_cvt_f32_f16_sdwa v153, v193 dst_sel:DWORD dst_unused:UNUSED_PAD src0_sel:WORD_1
	v_pk_fma_f32 v[100:101], v[130:131], v[146:147], v[100:101]
	v_pk_fma_f32 v[102:103], v[130:131], v[148:149], v[102:103]
	v_pk_fma_f32 v[96:97], v[130:131], v[150:151], v[96:97]
	v_pk_fma_f32 v[98:99], v[130:131], v[152:153], v[98:99]
	v_cvt_pk_f16_f32 v190, v100, v101
	v_cvt_pk_f16_f32 v191, v102, v103
	v_cvt_pk_f16_f32 v192, v96, v97
	v_cvt_pk_f16_f32 v193, v98, v99
	v_pk_mul_f32 v[100:101], v[100:101], v[100:101]
	v_pk_mul_f32 v[102:103], v[102:103], v[102:103]
	v_pk_mul_f32 v[96:97], v[96:97], v[96:97]
	v_pk_mul_f32 v[98:99], v[98:99], v[98:99]
	global_store_dwordx4 v163, v[190:193], s[8:9] offset:256 sc1
	s_nop 1
	v_add_f32_e32 v136, v100, v101
	v_add_f32_e32 v137, v102, v103
	v_add_f32_e32 v138, v96, v97
	v_add_f32_e32 v139, v98, v99
	v_add_f32_e32 v136, v136, v137
	v_add_f32_e32 v136, v138, v136
	v_add_f32_e32 v136, v139, v136
	v_add_f32_e32 v171, v171, v136
	s_mov_b64 exec, s[24:25]
	v_or_b32_e32 v128, 32, v132
	v_cmp_gt_i32_e64 s[0:1], s67, v128
	s_waitcnt vmcnt(21)
	v_mov_b32_e32 v130, v156
	v_mov_b32_e32 v131, v156
	s_and_saveexec_b64 s[24:25], s[0:1]
	s_waitcnt vmcnt(20)
	v_cvt_f32_f16_e32 v146, v194
	v_cvt_f32_f16_sdwa v147, v194 dst_sel:DWORD dst_unused:UNUSED_PAD src0_sel:WORD_1
	v_cvt_f32_f16_e32 v148, v195
	v_cvt_f32_f16_sdwa v149, v195 dst_sel:DWORD dst_unused:UNUSED_PAD src0_sel:WORD_1
	v_cvt_f32_f16_e32 v150, v196
	v_cvt_f32_f16_sdwa v151, v196 dst_sel:DWORD dst_unused:UNUSED_PAD src0_sel:WORD_1
	v_cvt_f32_f16_e32 v152, v197
	v_cvt_f32_f16_sdwa v153, v197 dst_sel:DWORD dst_unused:UNUSED_PAD src0_sel:WORD_1
	v_pk_fma_f32 v[92:93], v[130:131], v[146:147], v[92:93]
	v_pk_fma_f32 v[94:95], v[130:131], v[148:149], v[94:95]
	v_pk_fma_f32 v[88:89], v[130:131], v[150:151], v[88:89]
	v_pk_fma_f32 v[90:91], v[130:131], v[152:153], v[90:91]
	v_cvt_pk_f16_f32 v194, v92, v93
	v_cvt_pk_f16_f32 v195, v94, v95
	v_cvt_pk_f16_f32 v196, v88, v89
	v_cvt_pk_f16_f32 v197, v90, v91
	v_pk_mul_f32 v[92:93], v[92:93], v[92:93]
	v_pk_mul_f32 v[94:95], v[94:95], v[94:95]
	v_pk_mul_f32 v[88:89], v[88:89], v[88:89]
	v_pk_mul_f32 v[90:91], v[90:91], v[90:91]
	global_store_dwordx4 v164, v[194:197], s[8:9] sc1
	s_nop 1
	v_add_f32_e32 v136, v92, v93
	v_add_f32_e32 v137, v94, v95
	v_add_f32_e32 v138, v88, v89
	v_add_f32_e32 v139, v90, v91
	v_add_f32_e32 v136, v136, v137
	v_add_f32_e32 v136, v138, v136
	v_add_f32_e32 v172, v139, v136
	s_waitcnt vmcnt(20)
	v_cvt_f32_f16_e32 v146, v198
	v_cvt_f32_f16_sdwa v147, v198 dst_sel:DWORD dst_unused:UNUSED_PAD src0_sel:WORD_1
	v_cvt_f32_f16_e32 v148, v199
	v_cvt_f32_f16_sdwa v149, v199 dst_sel:DWORD dst_unused:UNUSED_PAD src0_sel:WORD_1
	v_cvt_f32_f16_e32 v150, v200
	v_cvt_f32_f16_sdwa v151, v200 dst_sel:DWORD dst_unused:UNUSED_PAD src0_sel:WORD_1
	v_cvt_f32_f16_e32 v152, v201
	v_cvt_f32_f16_sdwa v153, v201 dst_sel:DWORD dst_unused:UNUSED_PAD src0_sel:WORD_1
	v_pk_fma_f32 v[84:85], v[130:131], v[146:147], v[84:85]
	v_pk_fma_f32 v[86:87], v[130:131], v[148:149], v[86:87]
	v_pk_fma_f32 v[80:81], v[130:131], v[150:151], v[80:81]
	v_pk_fma_f32 v[82:83], v[130:131], v[152:153], v[82:83]
	v_cvt_pk_f16_f32 v198, v84, v85
	v_cvt_pk_f16_f32 v199, v86, v87
	v_cvt_pk_f16_f32 v200, v80, v81
	v_cvt_pk_f16_f32 v201, v82, v83
	v_pk_mul_f32 v[84:85], v[84:85], v[84:85]
	v_pk_mul_f32 v[86:87], v[86:87], v[86:87]
	v_pk_mul_f32 v[80:81], v[80:81], v[80:81]
	v_pk_mul_f32 v[82:83], v[82:83], v[82:83]
	global_store_dwordx4 v164, v[198:201], s[8:9] offset:256 sc1
	s_nop 1
	v_add_f32_e32 v136, v84, v85
	v_add_f32_e32 v137, v86, v87
	v_add_f32_e32 v138, v80, v81
	v_add_f32_e32 v139, v82, v83
	v_add_f32_e32 v136, v136, v137
	v_add_f32_e32 v136, v138, v136
	v_add_f32_e32 v136, v139, v136
	v_add_f32_e32 v172, v172, v136
	s_mov_b64 exec, s[24:25]
	v_or_b32_e32 v128, 48, v132
	v_cmp_gt_i32_e64 s[0:1], s67, v128
	s_waitcnt vmcnt(20)
	v_mov_b32_e32 v130, v157
	v_mov_b32_e32 v131, v157
	s_and_saveexec_b64 s[24:25], s[0:1]
	s_waitcnt vmcnt(19)
	v_cvt_f32_f16_e32 v146, v202
	v_cvt_f32_f16_sdwa v147, v202 dst_sel:DWORD dst_unused:UNUSED_PAD src0_sel:WORD_1
	v_cvt_f32_f16_e32 v148, v203
	v_cvt_f32_f16_sdwa v149, v203 dst_sel:DWORD dst_unused:UNUSED_PAD src0_sel:WORD_1
	v_cvt_f32_f16_e32 v150, v204
	v_cvt_f32_f16_sdwa v151, v204 dst_sel:DWORD dst_unused:UNUSED_PAD src0_sel:WORD_1
	v_cvt_f32_f16_e32 v152, v205
	v_cvt_f32_f16_sdwa v153, v205 dst_sel:DWORD dst_unused:UNUSED_PAD src0_sel:WORD_1
	v_pk_fma_f32 v[76:77], v[130:131], v[146:147], v[76:77]
	v_pk_fma_f32 v[78:79], v[130:131], v[148:149], v[78:79]
	v_pk_fma_f32 v[72:73], v[130:131], v[150:151], v[72:73]
	v_pk_fma_f32 v[74:75], v[130:131], v[152:153], v[74:75]
	v_cvt_pk_f16_f32 v202, v76, v77
	v_cvt_pk_f16_f32 v203, v78, v79
	v_cvt_pk_f16_f32 v204, v72, v73
	v_cvt_pk_f16_f32 v205, v74, v75
	v_pk_mul_f32 v[76:77], v[76:77], v[76:77]
	v_pk_mul_f32 v[78:79], v[78:79], v[78:79]
	v_pk_mul_f32 v[72:73], v[72:73], v[72:73]
	v_pk_mul_f32 v[74:75], v[74:75], v[74:75]
	global_store_dwordx4 v165, v[202:205], s[8:9] sc1
	s_nop 1
	v_add_f32_e32 v136, v76, v77
	v_add_f32_e32 v137, v78, v79
	v_add_f32_e32 v138, v72, v73
	v_add_f32_e32 v139, v74, v75
	v_add_f32_e32 v136, v136, v137
	v_add_f32_e32 v136, v138, v136
	v_add_f32_e32 v173, v139, v136
	s_waitcnt vmcnt(19)
	v_cvt_f32_f16_e32 v146, v206
	v_cvt_f32_f16_sdwa v147, v206 dst_sel:DWORD dst_unused:UNUSED_PAD src0_sel:WORD_1
	v_cvt_f32_f16_e32 v148, v207
	v_cvt_f32_f16_sdwa v149, v207 dst_sel:DWORD dst_unused:UNUSED_PAD src0_sel:WORD_1
	v_cvt_f32_f16_e32 v150, v208
	v_cvt_f32_f16_sdwa v151, v208 dst_sel:DWORD dst_unused:UNUSED_PAD src0_sel:WORD_1
	v_cvt_f32_f16_e32 v152, v209
	v_cvt_f32_f16_sdwa v153, v209 dst_sel:DWORD dst_unused:UNUSED_PAD src0_sel:WORD_1
	v_pk_fma_f32 v[68:69], v[130:131], v[146:147], v[68:69]
	v_pk_fma_f32 v[70:71], v[130:131], v[148:149], v[70:71]
	v_pk_fma_f32 v[64:65], v[130:131], v[150:151], v[64:65]
	v_pk_fma_f32 v[66:67], v[130:131], v[152:153], v[66:67]
	v_cvt_pk_f16_f32 v206, v68, v69
	v_cvt_pk_f16_f32 v207, v70, v71
	v_cvt_pk_f16_f32 v208, v64, v65
	v_cvt_pk_f16_f32 v209, v66, v67
	v_pk_mul_f32 v[68:69], v[68:69], v[68:69]
	v_pk_mul_f32 v[70:71], v[70:71], v[70:71]
	v_pk_mul_f32 v[64:65], v[64:65], v[64:65]
	v_pk_mul_f32 v[66:67], v[66:67], v[66:67]
	global_store_dwordx4 v165, v[206:209], s[8:9] offset:256 sc1
	s_nop 1
	v_add_f32_e32 v136, v68, v69
	v_add_f32_e32 v137, v70, v71
	v_add_f32_e32 v138, v64, v65
	v_add_f32_e32 v139, v66, v67
	v_add_f32_e32 v136, v136, v137
	v_add_f32_e32 v136, v138, v136
	v_add_f32_e32 v136, v139, v136
	v_add_f32_e32 v173, v173, v136
	s_mov_b64 exec, s[24:25]
	v_add_u32_e32 v128, 0x80, v132
	v_cmp_gt_i32_e64 s[0:1], s67, v128
	s_waitcnt vmcnt(19)
	v_mov_b32_e32 v130, v158
	v_mov_b32_e32 v131, v158
	s_and_saveexec_b64 s[24:25], s[0:1]
	s_waitcnt vmcnt(18)
	v_cvt_f32_f16_e32 v146, v210
	v_cvt_f32_f16_sdwa v147, v210 dst_sel:DWORD dst_unused:UNUSED_PAD src0_sel:WORD_1
	v_cvt_f32_f16_e32 v148, v211
	v_cvt_f32_f16_sdwa v149, v211 dst_sel:DWORD dst_unused:UNUSED_PAD src0_sel:WORD_1
	v_cvt_f32_f16_e32 v150, v212
	v_cvt_f32_f16_sdwa v151, v212 dst_sel:DWORD dst_unused:UNUSED_PAD src0_sel:WORD_1
	v_cvt_f32_f16_e32 v152, v213
	v_cvt_f32_f16_sdwa v153, v213 dst_sel:DWORD dst_unused:UNUSED_PAD src0_sel:WORD_1
	v_pk_fma_f32 v[60:61], v[130:131], v[146:147], v[60:61]
	v_pk_fma_f32 v[62:63], v[130:131], v[148:149], v[62:63]
	v_pk_fma_f32 v[56:57], v[130:131], v[150:151], v[56:57]
	v_pk_fma_f32 v[58:59], v[130:131], v[152:153], v[58:59]
	v_cvt_pk_f16_f32 v210, v60, v61
	v_cvt_pk_f16_f32 v211, v62, v63
	v_cvt_pk_f16_f32 v212, v56, v57
	v_cvt_pk_f16_f32 v213, v58, v59
	v_pk_mul_f32 v[60:61], v[60:61], v[60:61]
	v_pk_mul_f32 v[62:63], v[62:63], v[62:63]
	v_pk_mul_f32 v[56:57], v[56:57], v[56:57]
	v_pk_mul_f32 v[58:59], v[58:59], v[58:59]
	global_store_dwordx4 v166, v[210:213], s[8:9] sc1
	s_nop 1
	v_add_f32_e32 v136, v60, v61
	v_add_f32_e32 v137, v62, v63
	v_add_f32_e32 v138, v56, v57
	v_add_f32_e32 v139, v58, v59
	v_add_f32_e32 v136, v136, v137
	v_add_f32_e32 v136, v138, v136
	v_add_f32_e32 v174, v139, v136
	s_waitcnt vmcnt(18)
	v_cvt_f32_f16_e32 v146, v214
	v_cvt_f32_f16_sdwa v147, v214 dst_sel:DWORD dst_unused:UNUSED_PAD src0_sel:WORD_1
	v_cvt_f32_f16_e32 v148, v215
	v_cvt_f32_f16_sdwa v149, v215 dst_sel:DWORD dst_unused:UNUSED_PAD src0_sel:WORD_1
	v_cvt_f32_f16_e32 v150, v216
	v_cvt_f32_f16_sdwa v151, v216 dst_sel:DWORD dst_unused:UNUSED_PAD src0_sel:WORD_1
	v_cvt_f32_f16_e32 v152, v217
	v_cvt_f32_f16_sdwa v153, v217 dst_sel:DWORD dst_unused:UNUSED_PAD src0_sel:WORD_1
	v_pk_fma_f32 v[52:53], v[130:131], v[146:147], v[52:53]
	v_pk_fma_f32 v[54:55], v[130:131], v[148:149], v[54:55]
	v_pk_fma_f32 v[48:49], v[130:131], v[150:151], v[48:49]
	v_pk_fma_f32 v[50:51], v[130:131], v[152:153], v[50:51]
	v_cvt_pk_f16_f32 v214, v52, v53
	v_cvt_pk_f16_f32 v215, v54, v55
	v_cvt_pk_f16_f32 v216, v48, v49
	v_cvt_pk_f16_f32 v217, v50, v51
	v_pk_mul_f32 v[52:53], v[52:53], v[52:53]
	v_pk_mul_f32 v[54:55], v[54:55], v[54:55]
	v_pk_mul_f32 v[48:49], v[48:49], v[48:49]
	v_pk_mul_f32 v[50:51], v[50:51], v[50:51]
	global_store_dwordx4 v166, v[214:217], s[8:9] offset:256 sc1
	s_nop 1
	v_add_f32_e32 v136, v52, v53
	v_add_f32_e32 v137, v54, v55
	v_add_f32_e32 v138, v48, v49
	v_add_f32_e32 v139, v50, v51
	v_add_f32_e32 v136, v136, v137
	v_add_f32_e32 v136, v138, v136
	v_add_f32_e32 v136, v139, v136
	v_add_f32_e32 v174, v174, v136
	s_mov_b64 exec, s[24:25]
	v_add_u32_e32 v128, 0x90, v132
	v_cmp_gt_i32_e64 s[0:1], s67, v128
	s_waitcnt vmcnt(18)
	v_mov_b32_e32 v130, v159
	v_mov_b32_e32 v131, v159
	s_and_saveexec_b64 s[24:25], s[0:1]
	s_waitcnt vmcnt(17)
	v_cvt_f32_f16_e32 v146, v218
	v_cvt_f32_f16_sdwa v147, v218 dst_sel:DWORD dst_unused:UNUSED_PAD src0_sel:WORD_1
	v_cvt_f32_f16_e32 v148, v219
	v_cvt_f32_f16_sdwa v149, v219 dst_sel:DWORD dst_unused:UNUSED_PAD src0_sel:WORD_1
	v_cvt_f32_f16_e32 v150, v220
	v_cvt_f32_f16_sdwa v151, v220 dst_sel:DWORD dst_unused:UNUSED_PAD src0_sel:WORD_1
	v_cvt_f32_f16_e32 v152, v221
	v_cvt_f32_f16_sdwa v153, v221 dst_sel:DWORD dst_unused:UNUSED_PAD src0_sel:WORD_1
	v_pk_fma_f32 v[44:45], v[130:131], v[146:147], v[44:45]
	v_pk_fma_f32 v[46:47], v[130:131], v[148:149], v[46:47]
	v_pk_fma_f32 v[40:41], v[130:131], v[150:151], v[40:41]
	v_pk_fma_f32 v[42:43], v[130:131], v[152:153], v[42:43]
	v_cvt_pk_f16_f32 v218, v44, v45
	v_cvt_pk_f16_f32 v219, v46, v47
	v_cvt_pk_f16_f32 v220, v40, v41
	v_cvt_pk_f16_f32 v221, v42, v43
	v_pk_mul_f32 v[44:45], v[44:45], v[44:45]
	v_pk_mul_f32 v[46:47], v[46:47], v[46:47]
	v_pk_mul_f32 v[40:41], v[40:41], v[40:41]
	v_pk_mul_f32 v[42:43], v[42:43], v[42:43]
	global_store_dwordx4 v167, v[218:221], s[8:9] sc1
	s_nop 1
	v_add_f32_e32 v136, v44, v45
	v_add_f32_e32 v137, v46, v47
	v_add_f32_e32 v138, v40, v41
	v_add_f32_e32 v139, v42, v43
	v_add_f32_e32 v136, v136, v137
	v_add_f32_e32 v136, v138, v136
	v_add_f32_e32 v175, v139, v136
	s_waitcnt vmcnt(17)
	v_cvt_f32_f16_e32 v146, v222
	v_cvt_f32_f16_sdwa v147, v222 dst_sel:DWORD dst_unused:UNUSED_PAD src0_sel:WORD_1
	v_cvt_f32_f16_e32 v148, v223
	v_cvt_f32_f16_sdwa v149, v223 dst_sel:DWORD dst_unused:UNUSED_PAD src0_sel:WORD_1
	v_cvt_f32_f16_e32 v150, v224
	v_cvt_f32_f16_sdwa v151, v224 dst_sel:DWORD dst_unused:UNUSED_PAD src0_sel:WORD_1
	v_cvt_f32_f16_e32 v152, v225
	v_cvt_f32_f16_sdwa v153, v225 dst_sel:DWORD dst_unused:UNUSED_PAD src0_sel:WORD_1
	v_pk_fma_f32 v[36:37], v[130:131], v[146:147], v[36:37]
	v_pk_fma_f32 v[38:39], v[130:131], v[148:149], v[38:39]
	v_pk_fma_f32 v[32:33], v[130:131], v[150:151], v[32:33]
	v_pk_fma_f32 v[34:35], v[130:131], v[152:153], v[34:35]
	v_cvt_pk_f16_f32 v222, v36, v37
	v_cvt_pk_f16_f32 v223, v38, v39
	v_cvt_pk_f16_f32 v224, v32, v33
	v_cvt_pk_f16_f32 v225, v34, v35
	v_pk_mul_f32 v[36:37], v[36:37], v[36:37]
	v_pk_mul_f32 v[38:39], v[38:39], v[38:39]
	v_pk_mul_f32 v[32:33], v[32:33], v[32:33]
	v_pk_mul_f32 v[34:35], v[34:35], v[34:35]
	global_store_dwordx4 v167, v[222:225], s[8:9] offset:256 sc1
	s_nop 1
	v_add_f32_e32 v136, v36, v37
	v_add_f32_e32 v137, v38, v39
	v_add_f32_e32 v138, v32, v33
	v_add_f32_e32 v139, v34, v35
	v_add_f32_e32 v136, v136, v137
	v_add_f32_e32 v136, v138, v136
	v_add_f32_e32 v136, v139, v136
	v_add_f32_e32 v175, v175, v136
	s_mov_b64 exec, s[24:25]
	v_add_u32_e32 v128, 0xa0, v132
	v_cmp_gt_i32_e64 s[0:1], s67, v128
	s_waitcnt vmcnt(17)
	v_mov_b32_e32 v130, v160
	v_mov_b32_e32 v131, v160
	s_and_saveexec_b64 s[24:25], s[0:1]
	s_waitcnt vmcnt(16)
	v_cvt_f32_f16_e32 v146, v226
	v_cvt_f32_f16_sdwa v147, v226 dst_sel:DWORD dst_unused:UNUSED_PAD src0_sel:WORD_1
	v_cvt_f32_f16_e32 v148, v227
	v_cvt_f32_f16_sdwa v149, v227 dst_sel:DWORD dst_unused:UNUSED_PAD src0_sel:WORD_1
	v_cvt_f32_f16_e32 v150, v228
	v_cvt_f32_f16_sdwa v151, v228 dst_sel:DWORD dst_unused:UNUSED_PAD src0_sel:WORD_1
	v_cvt_f32_f16_e32 v152, v229
	v_cvt_f32_f16_sdwa v153, v229 dst_sel:DWORD dst_unused:UNUSED_PAD src0_sel:WORD_1
	v_pk_fma_f32 v[28:29], v[130:131], v[146:147], v[28:29]
	v_pk_fma_f32 v[30:31], v[130:131], v[148:149], v[30:31]
	v_pk_fma_f32 v[24:25], v[130:131], v[150:151], v[24:25]
	v_pk_fma_f32 v[26:27], v[130:131], v[152:153], v[26:27]
	v_cvt_pk_f16_f32 v226, v28, v29
	v_cvt_pk_f16_f32 v227, v30, v31
	v_cvt_pk_f16_f32 v228, v24, v25
	v_cvt_pk_f16_f32 v229, v26, v27
	v_pk_mul_f32 v[28:29], v[28:29], v[28:29]
	v_pk_mul_f32 v[30:31], v[30:31], v[30:31]
	v_pk_mul_f32 v[24:25], v[24:25], v[24:25]
	v_pk_mul_f32 v[26:27], v[26:27], v[26:27]
	global_store_dwordx4 v168, v[226:229], s[8:9] sc1
	s_nop 1
	v_add_f32_e32 v136, v28, v29
	v_add_f32_e32 v137, v30, v31
	v_add_f32_e32 v138, v24, v25
	v_add_f32_e32 v139, v26, v27
	v_add_f32_e32 v136, v136, v137
	v_add_f32_e32 v136, v138, v136
	v_add_f32_e32 v176, v139, v136
	s_waitcnt vmcnt(16)
	v_cvt_f32_f16_e32 v146, v230
	v_cvt_f32_f16_sdwa v147, v230 dst_sel:DWORD dst_unused:UNUSED_PAD src0_sel:WORD_1
	v_cvt_f32_f16_e32 v148, v231
	v_cvt_f32_f16_sdwa v149, v231 dst_sel:DWORD dst_unused:UNUSED_PAD src0_sel:WORD_1
	v_cvt_f32_f16_e32 v150, v232
	v_cvt_f32_f16_sdwa v151, v232 dst_sel:DWORD dst_unused:UNUSED_PAD src0_sel:WORD_1
	v_cvt_f32_f16_e32 v152, v233
	v_cvt_f32_f16_sdwa v153, v233 dst_sel:DWORD dst_unused:UNUSED_PAD src0_sel:WORD_1
	v_pk_fma_f32 v[20:21], v[130:131], v[146:147], v[20:21]
	v_pk_fma_f32 v[22:23], v[130:131], v[148:149], v[22:23]
	v_pk_fma_f32 v[16:17], v[130:131], v[150:151], v[16:17]
	v_pk_fma_f32 v[18:19], v[130:131], v[152:153], v[18:19]
	v_cvt_pk_f16_f32 v230, v20, v21
	v_cvt_pk_f16_f32 v231, v22, v23
	v_cvt_pk_f16_f32 v232, v16, v17
	v_cvt_pk_f16_f32 v233, v18, v19
	v_pk_mul_f32 v[20:21], v[20:21], v[20:21]
	v_pk_mul_f32 v[22:23], v[22:23], v[22:23]
	v_pk_mul_f32 v[16:17], v[16:17], v[16:17]
	v_pk_mul_f32 v[18:19], v[18:19], v[18:19]
	global_store_dwordx4 v168, v[230:233], s[8:9] offset:256 sc1
	s_nop 1
	v_add_f32_e32 v136, v20, v21
	v_add_f32_e32 v137, v22, v23
	v_add_f32_e32 v138, v16, v17
	v_add_f32_e32 v139, v18, v19
	v_add_f32_e32 v136, v136, v137
	v_add_f32_e32 v136, v138, v136
	v_add_f32_e32 v136, v139, v136
	v_add_f32_e32 v176, v176, v136
	s_mov_b64 exec, s[24:25]
	v_add_u32_e32 v128, 0xb0, v132
	v_cmp_gt_i32_e64 s[0:1], s67, v128
	s_waitcnt vmcnt(16)
	v_mov_b32_e32 v130, v161
	v_mov_b32_e32 v131, v161
	s_and_saveexec_b64 s[24:25], s[0:1]
	s_waitcnt vmcnt(15)
	v_cvt_f32_f16_e32 v146, v234
	v_cvt_f32_f16_sdwa v147, v234 dst_sel:DWORD dst_unused:UNUSED_PAD src0_sel:WORD_1
	v_cvt_f32_f16_e32 v148, v235
	v_cvt_f32_f16_sdwa v149, v235 dst_sel:DWORD dst_unused:UNUSED_PAD src0_sel:WORD_1
	v_cvt_f32_f16_e32 v150, v236
	v_cvt_f32_f16_sdwa v151, v236 dst_sel:DWORD dst_unused:UNUSED_PAD src0_sel:WORD_1
	v_cvt_f32_f16_e32 v152, v237
	v_cvt_f32_f16_sdwa v153, v237 dst_sel:DWORD dst_unused:UNUSED_PAD src0_sel:WORD_1
	v_pk_fma_f32 v[12:13], v[130:131], v[146:147], v[12:13]
	v_pk_fma_f32 v[14:15], v[130:131], v[148:149], v[14:15]
	v_pk_fma_f32 v[8:9], v[130:131], v[150:151], v[8:9]
	v_pk_fma_f32 v[10:11], v[130:131], v[152:153], v[10:11]
	v_cvt_pk_f16_f32 v234, v12, v13
	v_cvt_pk_f16_f32 v235, v14, v15
	v_cvt_pk_f16_f32 v236, v8, v9
	v_cvt_pk_f16_f32 v237, v10, v11
	v_pk_mul_f32 v[12:13], v[12:13], v[12:13]
	v_pk_mul_f32 v[14:15], v[14:15], v[14:15]
	v_pk_mul_f32 v[8:9], v[8:9], v[8:9]
	v_pk_mul_f32 v[10:11], v[10:11], v[10:11]
	global_store_dwordx4 v169, v[234:237], s[8:9] sc1
	s_nop 1
	v_add_f32_e32 v136, v12, v13
	v_add_f32_e32 v137, v14, v15
	v_add_f32_e32 v138, v8, v9
	v_add_f32_e32 v139, v10, v11
	v_add_f32_e32 v136, v136, v137
	v_add_f32_e32 v136, v138, v136
	v_add_f32_e32 v177, v139, v136
	s_waitcnt vmcnt(15)
	v_cvt_f32_f16_e32 v146, v238
	v_cvt_f32_f16_sdwa v147, v238 dst_sel:DWORD dst_unused:UNUSED_PAD src0_sel:WORD_1
	v_cvt_f32_f16_e32 v148, v239
	v_cvt_f32_f16_sdwa v149, v239 dst_sel:DWORD dst_unused:UNUSED_PAD src0_sel:WORD_1
	v_cvt_f32_f16_e32 v150, v240
	v_cvt_f32_f16_sdwa v151, v240 dst_sel:DWORD dst_unused:UNUSED_PAD src0_sel:WORD_1
	v_cvt_f32_f16_e32 v152, v241
	v_cvt_f32_f16_sdwa v153, v241 dst_sel:DWORD dst_unused:UNUSED_PAD src0_sel:WORD_1
	v_pk_fma_f32 v[4:5], v[130:131], v[146:147], v[4:5]
	v_pk_fma_f32 v[6:7], v[130:131], v[148:149], v[6:7]
	v_pk_fma_f32 v[0:1], v[130:131], v[150:151], v[0:1]
	v_pk_fma_f32 v[2:3], v[130:131], v[152:153], v[2:3]
	v_cvt_pk_f16_f32 v238, v4, v5
	v_cvt_pk_f16_f32 v239, v6, v7
	v_cvt_pk_f16_f32 v240, v0, v1
	v_cvt_pk_f16_f32 v241, v2, v3
	v_pk_mul_f32 v[4:5], v[4:5], v[4:5]
	v_pk_mul_f32 v[6:7], v[6:7], v[6:7]
	v_pk_mul_f32 v[0:1], v[0:1], v[0:1]
	v_pk_mul_f32 v[2:3], v[2:3], v[2:3]
	global_store_dwordx4 v169, v[238:241], s[8:9] offset:256 sc1
	s_nop 1
	v_add_f32_e32 v136, v4, v5
	v_add_f32_e32 v137, v6, v7
	v_add_f32_e32 v138, v0, v1
	v_add_f32_e32 v139, v2, v3
	v_add_f32_e32 v136, v136, v137
	v_add_f32_e32 v136, v138, v136
	v_add_f32_e32 v136, v139, v136
	v_add_f32_e32 v177, v177, v136
	s_mov_b64 exec, s[24:25]
	ds_bpermute_b32 v242, v134, v170
	ds_bpermute_b32 v243, v134, v171
	ds_bpermute_b32 v244, v134, v172
	ds_bpermute_b32 v245, v134, v173
	ds_bpermute_b32 v246, v134, v174
	ds_bpermute_b32 v247, v134, v175
	ds_bpermute_b32 v248, v134, v176
	ds_bpermute_b32 v249, v134, v177
	s_waitcnt lgkmcnt(7)
	v_add_f32_e32 v242, v170, v242
	s_waitcnt lgkmcnt(6)
	v_add_f32_e32 v243, v171, v243
	s_waitcnt lgkmcnt(5)
	v_add_f32_e32 v244, v172, v244
	s_waitcnt lgkmcnt(4)
	v_add_f32_e32 v245, v173, v245
	s_waitcnt lgkmcnt(3)
	v_add_f32_e32 v246, v174, v246
	s_waitcnt lgkmcnt(2)
	v_add_f32_e32 v247, v175, v247
	s_waitcnt lgkmcnt(1)
	v_add_f32_e32 v248, v176, v248
	s_waitcnt lgkmcnt(0)
	v_add_f32_e32 v249, v177, v249
	s_nop 0
	ds_bpermute_b32 v0, v135, v242
	ds_bpermute_b32 v1, v135, v243
	ds_bpermute_b32 v2, v135, v244
	ds_bpermute_b32 v3, v135, v245
	ds_bpermute_b32 v4, v135, v246
	ds_bpermute_b32 v5, v135, v247
	ds_bpermute_b32 v6, v135, v248
	ds_bpermute_b32 v7, v135, v249
	v_cmp_gt_i32_e64 s[0:1], s67, v132
	v_lshl_or_b32 v8, v132, 4, s26
	v_lshlrev_b32_e32 v8, 2, v8
	s_and_b64 s[24:25], vcc, s[0:1]
	s_and_saveexec_b64 s[0:1], s[24:25]
	s_waitcnt lgkmcnt(7)
	v_add_f32_e32 v242, v242, v0
	global_store_dword v8, v242, s[4:5] sc1
	s_mov_b64 exec, s[0:1]
	v_or_b32_e32 v128, 16, v132
	v_cmp_gt_i32_e64 s[0:1], s67, v128
	v_lshl_or_b32 v9, v128, 4, s26
	v_lshlrev_b32_e32 v9, 2, v9
	s_and_b64 s[24:25], vcc, s[0:1]
	s_and_saveexec_b64 s[0:1], s[24:25]
	s_waitcnt lgkmcnt(6)
	v_add_f32_e32 v243, v243, v1
	global_store_dword v9, v243, s[4:5] sc1
	s_mov_b64 exec, s[0:1]
	v_or_b32_e32 v128, 32, v132
	v_cmp_gt_i32_e64 s[0:1], s67, v128
	v_lshl_or_b32 v10, v128, 4, s26
	v_lshlrev_b32_e32 v10, 2, v10
	s_and_b64 s[24:25], vcc, s[0:1]
	s_and_saveexec_b64 s[0:1], s[24:25]
	s_waitcnt lgkmcnt(5)
	v_add_f32_e32 v244, v244, v2
	global_store_dword v10, v244, s[4:5] sc1
	s_mov_b64 exec, s[0:1]
	v_or_b32_e32 v128, 48, v132
	v_cmp_gt_i32_e64 s[0:1], s67, v128
	v_lshl_or_b32 v11, v128, 4, s26
	v_lshlrev_b32_e32 v11, 2, v11
	s_and_b64 s[24:25], vcc, s[0:1]
	s_and_saveexec_b64 s[0:1], s[24:25]
	s_waitcnt lgkmcnt(4)
	v_add_f32_e32 v245, v245, v3
	global_store_dword v11, v245, s[4:5] sc1
	s_mov_b64 exec, s[0:1]
	v_add_u32_e32 v128, 0x80, v132
	v_cmp_gt_i32_e64 s[0:1], s67, v128
	v_lshl_or_b32 v12, v128, 4, s26
	v_lshlrev_b32_e32 v12, 2, v12
	s_and_b64 s[24:25], vcc, s[0:1]
	s_and_saveexec_b64 s[0:1], s[24:25]
	s_waitcnt lgkmcnt(3)
	v_add_f32_e32 v246, v246, v4
	global_store_dword v12, v246, s[4:5] sc1
	s_mov_b64 exec, s[0:1]
	v_add_u32_e32 v128, 0x90, v132
	v_cmp_gt_i32_e64 s[0:1], s67, v128
	v_lshl_or_b32 v13, v128, 4, s26
	v_lshlrev_b32_e32 v13, 2, v13
	s_and_b64 s[24:25], vcc, s[0:1]
	s_and_saveexec_b64 s[0:1], s[24:25]
	s_waitcnt lgkmcnt(2)
	v_add_f32_e32 v247, v247, v5
	global_store_dword v13, v247, s[4:5] sc1
	s_mov_b64 exec, s[0:1]
	v_add_u32_e32 v128, 0xa0, v132
	v_cmp_gt_i32_e64 s[0:1], s67, v128
	v_lshl_or_b32 v14, v128, 4, s26
	v_lshlrev_b32_e32 v14, 2, v14
	s_and_b64 s[24:25], vcc, s[0:1]
	s_and_saveexec_b64 s[0:1], s[24:25]
	s_waitcnt lgkmcnt(1)
	v_add_f32_e32 v248, v248, v6
	global_store_dword v14, v248, s[4:5] sc1
	s_mov_b64 exec, s[0:1]
	v_add_u32_e32 v128, 0xb0, v132
	v_cmp_gt_i32_e64 s[0:1], s67, v128
	v_lshl_or_b32 v15, v128, 4, s26
	v_lshlrev_b32_e32 v15, 2, v15
	s_and_b64 s[24:25], vcc, s[0:1]
	s_and_saveexec_b64 s[0:1], s[24:25]
	s_waitcnt lgkmcnt(0)
	v_add_f32_e32 v249, v249, v7
	global_store_dword v15, v249, s[4:5] sc1
	s_mov_b64 exec, s[0:1]
	s_waitcnt vmcnt(0)
	s_barrier
	v_mbcnt_lo_u32_b32 v0, -1, 0
	v_mbcnt_hi_u32_b32 v0, -1, v0
	s_nop 0
	v_or_b32_e32 v0, s97, v0
	v_cmp_eq_u32_e32 vcc, 0, v0
	s_and_saveexec_b64 s[0:1], vcc
	s_xor_b64 s[0:1], exec, s[0:1]
	s_cbranch_execz .LBB0_1293
	s_mov_b64 s[24:25], exec
	v_mbcnt_lo_u32_b32 v0, s24, 0
	v_mbcnt_hi_u32_b32 v0, s25, v0
	v_cmp_eq_u32_e32 vcc, 0, v0
	s_and_saveexec_b64 s[26:27], vcc
	s_xor_b64 s[26:27], exec, s[26:27]
	s_cbranch_execz .LBB0_1292
	s_lshl_b32 s18, s18, 6
	s_lshl_b64 s[28:29], s[18:19], 2
	s_add_u32 s28, s58, s28
	s_addc_u32 s29, s59, s29
	s_bcnt1_i32_b64 s18, s[24:25]
	v_mov_b32_e32 v0, s18
	global_atomic_add v129, v0, s[28:29]
	s_branch .LBB0_1292

.LBB0_1471:
	v_mov_b32_e32 v155, v144
	v_mov_b32_e32 v154, v145
	v_readlane_b32 s92, v255, 4
	v_readlane_b32 s93, v255, 5
	v_readlane_b32 s94, v255, 6
	v_readlane_b32 s95, v255, 7
	v_lshlrev_b32_e32 v136, 4, v154
	v_add_u32_e32 v156, s56, v155
	v_add_u32_e32 v142, s57, v136
	v_lshl_add_u32 v153, s50, 8, v156
	v_lshl_add_u32 v142, s30, 9, v142
	v_lshlrev_b32_e32 v161, 4, v156
	v_add_u32_e32 v161, s78, v161
	v_cmp_gt_i32_e64 s[6:7], s86, v153
	v_mov_b32_e32 v246, 0
	s_nop 0
	v_cndmask_b32_e64 v143, 0, v153, s[6:7]
	v_lshl_add_u32 v143, v143, 11, v142
	global_load_dwordx4 v[174:177], v143, s[28:29]
	global_load_dwordx4 v[178:181], v143, s[24:25]
	global_load_dwordx4 v[182:185], v143, s[28:29] offset:256
	global_load_dwordx4 v[186:189], v143, s[24:25] offset:256
	v_add_u32_e32 v156, 16, v153
	v_cmp_gt_i32_e64 s[8:9], s86, v156
	v_mov_b32_e32 v247, 0
	s_nop 0
	v_cndmask_b32_e64 v143, 0, v156, s[8:9]
	v_lshl_add_u32 v143, v143, 11, v142
	global_load_dwordx4 v[190:193], v143, s[28:29]
	global_load_dwordx4 v[194:197], v143, s[24:25]
	global_load_dwordx4 v[198:201], v143, s[28:29] offset:256
	global_load_dwordx4 v[202:205], v143, s[24:25] offset:256
	v_add_u32_e32 v157, 32, v153
	v_cmp_gt_i32_e64 s[10:11], s86, v157
	v_mov_b32_e32 v248, 0
	s_nop 0
	v_cndmask_b32_e64 v143, 0, v157, s[10:11]
	v_lshl_add_u32 v143, v143, 11, v142
	global_load_dwordx4 v[206:209], v143, s[28:29]
	global_load_dwordx4 v[210:213], v143, s[24:25]
	global_load_dwordx4 v[214:217], v143, s[28:29] offset:256
	global_load_dwordx4 v[218:221], v143, s[24:25] offset:256
	v_add_u32_e32 v158, 48, v153
	v_cmp_gt_i32_e64 s[12:13], s86, v158
	v_mov_b32_e32 v249, 0
	s_nop 0
	v_cndmask_b32_e64 v143, 0, v158, s[12:13]
	v_lshl_add_u32 v143, v143, 11, v142
	global_load_dwordx4 v[222:225], v143, s[28:29]
	global_load_dwordx4 v[226:229], v143, s[24:25]
	global_load_dwordx4 v[230:233], v143, s[28:29] offset:256
	global_load_dwordx4 v[234:237], v143, s[24:25] offset:256
	s_and_saveexec_b64 s[22:23], s[6:7]
	s_waitcnt vmcnt(14)
	v_cvt_f32_f16_e32 v166, v174
	v_cvt_f32_f16_sdwa v167, v174 dst_sel:DWORD dst_unused:UNUSED_PAD src0_sel:WORD_1
	v_cvt_f32_f16_e32 v168, v175
	v_cvt_f32_f16_sdwa v169, v175 dst_sel:DWORD dst_unused:UNUSED_PAD src0_sel:WORD_1
	v_cvt_f32_f16_e32 v170, v176
	v_cvt_f32_f16_sdwa v171, v176 dst_sel:DWORD dst_unused:UNUSED_PAD src0_sel:WORD_1
	v_cvt_f32_f16_e32 v172, v177
	v_cvt_f32_f16_sdwa v173, v177 dst_sel:DWORD dst_unused:UNUSED_PAD src0_sel:WORD_1
	v_cvt_f32_f16_e32 v238, v178
	v_cvt_f32_f16_sdwa v239, v178 dst_sel:DWORD dst_unused:UNUSED_PAD src0_sel:WORD_1
	v_cvt_f32_f16_e32 v240, v179
	v_cvt_f32_f16_sdwa v241, v179 dst_sel:DWORD dst_unused:UNUSED_PAD src0_sel:WORD_1
	v_cvt_f32_f16_e32 v242, v180
	v_cvt_f32_f16_sdwa v243, v180 dst_sel:DWORD dst_unused:UNUSED_PAD src0_sel:WORD_1
	v_cvt_f32_f16_e32 v244, v181
	v_cvt_f32_f16_sdwa v245, v181 dst_sel:DWORD dst_unused:UNUSED_PAD src0_sel:WORD_1
	v_pk_fma_f32 v[124:125], v[124:125], v[166:167], v[238:239]
	v_pk_fma_f32 v[126:127], v[126:127], v[168:169], v[240:241]
	v_pk_fma_f32 v[116:117], v[116:117], v[170:171], v[242:243]
	v_pk_fma_f32 v[118:119], v[118:119], v[172:173], v[244:245]
	v_pk_mul_f32 v[166:167], v[124:125], v[124:125]
	v_pk_mul_f32 v[168:169], v[126:127], v[126:127]
	v_pk_mul_f32 v[170:171], v[116:117], v[116:117]
	v_pk_mul_f32 v[172:173], v[118:119], v[118:119]
	v_add_f32_e32 v152, v166, v167
	v_add_f32_e32 v160, v168, v169
	v_add_f32_e32 v152, v152, v160
	v_add_f32_e32 v160, v170, v171
	v_add_f32_e32 v152, v160, v152
	v_add_f32_e32 v160, v172, v173
	v_add_f32_e32 v246, v160, v152
	s_waitcnt vmcnt(12)
	v_cvt_f32_f16_e32 v166, v182
	v_cvt_f32_f16_sdwa v167, v182 dst_sel:DWORD dst_unused:UNUSED_PAD src0_sel:WORD_1
	v_cvt_f32_f16_e32 v168, v183
	v_cvt_f32_f16_sdwa v169, v183 dst_sel:DWORD dst_unused:UNUSED_PAD src0_sel:WORD_1
	v_cvt_f32_f16_e32 v170, v184
	v_cvt_f32_f16_sdwa v171, v184 dst_sel:DWORD dst_unused:UNUSED_PAD src0_sel:WORD_1
	v_cvt_f32_f16_e32 v172, v185
	v_cvt_f32_f16_sdwa v173, v185 dst_sel:DWORD dst_unused:UNUSED_PAD src0_sel:WORD_1
	v_cvt_f32_f16_e32 v238, v186
	v_cvt_f32_f16_sdwa v239, v186 dst_sel:DWORD dst_unused:UNUSED_PAD src0_sel:WORD_1
	v_cvt_f32_f16_e32 v240, v187
	v_cvt_f32_f16_sdwa v241, v187 dst_sel:DWORD dst_unused:UNUSED_PAD src0_sel:WORD_1
	v_cvt_f32_f16_e32 v242, v188
	v_cvt_f32_f16_sdwa v243, v188 dst_sel:DWORD dst_unused:UNUSED_PAD src0_sel:WORD_1
	v_cvt_f32_f16_e32 v244, v189
	v_cvt_f32_f16_sdwa v245, v189 dst_sel:DWORD dst_unused:UNUSED_PAD src0_sel:WORD_1
	v_pk_fma_f32 v[120:121], v[120:121], v[166:167], v[238:239]
	v_pk_fma_f32 v[122:123], v[122:123], v[168:169], v[240:241]
	v_pk_fma_f32 v[112:113], v[112:113], v[170:171], v[242:243]
	v_pk_fma_f32 v[114:115], v[114:115], v[172:173], v[244:245]
	v_pk_mul_f32 v[166:167], v[120:121], v[120:121]
	v_pk_mul_f32 v[168:169], v[122:123], v[122:123]
	v_pk_mul_f32 v[170:171], v[112:113], v[112:113]
	v_pk_mul_f32 v[172:173], v[114:115], v[114:115]
	v_add_f32_e32 v152, v166, v167
	v_add_f32_e32 v160, v168, v169
	v_add_f32_e32 v152, v152, v160
	v_add_f32_e32 v160, v170, v171
	v_add_f32_e32 v152, v160, v152
	v_add_f32_e32 v160, v172, v173
	v_add_f32_e32 v152, v160, v152
	v_add_f32_e32 v246, v246, v152
	s_mov_b64 exec, s[22:23]
	v_add_u32_e32 v159, 0x80, v153
	v_cmp_gt_i32_e64 s[14:15], s86, v159
	v_mov_b32_e32 v250, 0
	s_nop 0
	v_cndmask_b32_e64 v143, 0, v159, s[14:15]
	v_lshl_add_u32 v143, v143, 11, v142
	global_load_dwordx4 v[174:177], v143, s[28:29]
	global_load_dwordx4 v[178:181], v143, s[24:25]
	global_load_dwordx4 v[182:185], v143, s[28:29] offset:256
	global_load_dwordx4 v[186:189], v143, s[24:25] offset:256
	s_and_saveexec_b64 s[22:23], s[8:9]
	s_waitcnt vmcnt(14)
	v_cvt_f32_f16_e32 v166, v190
	v_cvt_f32_f16_sdwa v167, v190 dst_sel:DWORD dst_unused:UNUSED_PAD src0_sel:WORD_1
	v_cvt_f32_f16_e32 v168, v191
	v_cvt_f32_f16_sdwa v169, v191 dst_sel:DWORD dst_unused:UNUSED_PAD src0_sel:WORD_1
	v_cvt_f32_f16_e32 v170, v192
	v_cvt_f32_f16_sdwa v171, v192 dst_sel:DWORD dst_unused:UNUSED_PAD src0_sel:WORD_1
	v_cvt_f32_f16_e32 v172, v193
	v_cvt_f32_f16_sdwa v173, v193 dst_sel:DWORD dst_unused:UNUSED_PAD src0_sel:WORD_1
	v_cvt_f32_f16_e32 v238, v194
	v_cvt_f32_f16_sdwa v239, v194 dst_sel:DWORD dst_unused:UNUSED_PAD src0_sel:WORD_1
	v_cvt_f32_f16_e32 v240, v195
	v_cvt_f32_f16_sdwa v241, v195 dst_sel:DWORD dst_unused:UNUSED_PAD src0_sel:WORD_1
	v_cvt_f32_f16_e32 v242, v196
	v_cvt_f32_f16_sdwa v243, v196 dst_sel:DWORD dst_unused:UNUSED_PAD src0_sel:WORD_1
	v_cvt_f32_f16_e32 v244, v197
	v_cvt_f32_f16_sdwa v245, v197 dst_sel:DWORD dst_unused:UNUSED_PAD src0_sel:WORD_1
	v_pk_fma_f32 v[108:109], v[108:109], v[166:167], v[238:239]
	v_pk_fma_f32 v[110:111], v[110:111], v[168:169], v[240:241]
	v_pk_fma_f32 v[100:101], v[100:101], v[170:171], v[242:243]
	v_pk_fma_f32 v[102:103], v[102:103], v[172:173], v[244:245]
	v_pk_mul_f32 v[166:167], v[108:109], v[108:109]
	v_pk_mul_f32 v[168:169], v[110:111], v[110:111]
	v_pk_mul_f32 v[170:171], v[100:101], v[100:101]
	v_pk_mul_f32 v[172:173], v[102:103], v[102:103]
	v_add_f32_e32 v152, v166, v167
	v_add_f32_e32 v160, v168, v169
	v_add_f32_e32 v152, v152, v160
	v_add_f32_e32 v160, v170, v171
	v_add_f32_e32 v152, v160, v152
	v_add_f32_e32 v160, v172, v173
	v_add_f32_e32 v247, v160, v152
	s_waitcnt vmcnt(12)
	v_cvt_f32_f16_e32 v166, v198
	v_cvt_f32_f16_sdwa v167, v198 dst_sel:DWORD dst_unused:UNUSED_PAD src0_sel:WORD_1
	v_cvt_f32_f16_e32 v168, v199
	v_cvt_f32_f16_sdwa v169, v199 dst_sel:DWORD dst_unused:UNUSED_PAD src0_sel:WORD_1
	v_cvt_f32_f16_e32 v170, v200
	v_cvt_f32_f16_sdwa v171, v200 dst_sel:DWORD dst_unused:UNUSED_PAD src0_sel:WORD_1
	v_cvt_f32_f16_e32 v172, v201
	v_cvt_f32_f16_sdwa v173, v201 dst_sel:DWORD dst_unused:UNUSED_PAD src0_sel:WORD_1
	v_cvt_f32_f16_e32 v238, v202
	v_cvt_f32_f16_sdwa v239, v202 dst_sel:DWORD dst_unused:UNUSED_PAD src0_sel:WORD_1
	v_cvt_f32_f16_e32 v240, v203
	v_cvt_f32_f16_sdwa v241, v203 dst_sel:DWORD dst_unused:UNUSED_PAD src0_sel:WORD_1
	v_cvt_f32_f16_e32 v242, v204
	v_cvt_f32_f16_sdwa v243, v204 dst_sel:DWORD dst_unused:UNUSED_PAD src0_sel:WORD_1
	v_cvt_f32_f16_e32 v244, v205
	v_cvt_f32_f16_sdwa v245, v205 dst_sel:DWORD dst_unused:UNUSED_PAD src0_sel:WORD_1
	v_pk_fma_f32 v[104:105], v[104:105], v[166:167], v[238:239]
	v_pk_fma_f32 v[106:107], v[106:107], v[168:169], v[240:241]
	v_pk_fma_f32 v[96:97], v[96:97], v[170:171], v[242:243]
	v_pk_fma_f32 v[98:99], v[98:99], v[172:173], v[244:245]
	v_pk_mul_f32 v[166:167], v[104:105], v[104:105]
	v_pk_mul_f32 v[168:169], v[106:107], v[106:107]
	v_pk_mul_f32 v[170:171], v[96:97], v[96:97]
	v_pk_mul_f32 v[172:173], v[98:99], v[98:99]
	v_add_f32_e32 v152, v166, v167
	v_add_f32_e32 v160, v168, v169
	v_add_f32_e32 v152, v152, v160
	v_add_f32_e32 v160, v170, v171
	v_add_f32_e32 v152, v160, v152
	v_add_f32_e32 v160, v172, v173
	v_add_f32_e32 v152, v160, v152
	v_add_f32_e32 v247, v247, v152
	s_mov_b64 exec, s[22:23]
	v_add_u32_e32 v162, 0x90, v153
	v_cmp_gt_i32_e64 s[16:17], s86, v162
	v_mov_b32_e32 v251, 0
	s_nop 0
	v_cndmask_b32_e64 v143, 0, v162, s[16:17]
	v_lshl_add_u32 v143, v143, 11, v142
	global_load_dwordx4 v[190:193], v143, s[28:29]
	global_load_dwordx4 v[194:197], v143, s[24:25]
	global_load_dwordx4 v[198:201], v143, s[28:29] offset:256
	global_load_dwordx4 v[202:205], v143, s[24:25] offset:256
	s_and_saveexec_b64 s[22:23], s[10:11]
	s_waitcnt vmcnt(14)
	v_cvt_f32_f16_e32 v166, v206
	v_cvt_f32_f16_sdwa v167, v206 dst_sel:DWORD dst_unused:UNUSED_PAD src0_sel:WORD_1
	v_cvt_f32_f16_e32 v168, v207
	v_cvt_f32_f16_sdwa v169, v207 dst_sel:DWORD dst_unused:UNUSED_PAD src0_sel:WORD_1
	v_cvt_f32_f16_e32 v170, v208
	v_cvt_f32_f16_sdwa v171, v208 dst_sel:DWORD dst_unused:UNUSED_PAD src0_sel:WORD_1
	v_cvt_f32_f16_e32 v172, v209
	v_cvt_f32_f16_sdwa v173, v209 dst_sel:DWORD dst_unused:UNUSED_PAD src0_sel:WORD_1
	v_cvt_f32_f16_e32 v238, v210
	v_cvt_f32_f16_sdwa v239, v210 dst_sel:DWORD dst_unused:UNUSED_PAD src0_sel:WORD_1
	v_cvt_f32_f16_e32 v240, v211
	v_cvt_f32_f16_sdwa v241, v211 dst_sel:DWORD dst_unused:UNUSED_PAD src0_sel:WORD_1
	v_cvt_f32_f16_e32 v242, v212
	v_cvt_f32_f16_sdwa v243, v212 dst_sel:DWORD dst_unused:UNUSED_PAD src0_sel:WORD_1
	v_cvt_f32_f16_e32 v244, v213
	v_cvt_f32_f16_sdwa v245, v213 dst_sel:DWORD dst_unused:UNUSED_PAD src0_sel:WORD_1
	v_pk_fma_f32 v[92:93], v[92:93], v[166:167], v[238:239]
	v_pk_fma_f32 v[94:95], v[94:95], v[168:169], v[240:241]
	v_pk_fma_f32 v[84:85], v[84:85], v[170:171], v[242:243]
	v_pk_fma_f32 v[86:87], v[86:87], v[172:173], v[244:245]
	v_pk_mul_f32 v[166:167], v[92:93], v[92:93]
	v_pk_mul_f32 v[168:169], v[94:95], v[94:95]
	v_pk_mul_f32 v[170:171], v[84:85], v[84:85]
	v_pk_mul_f32 v[172:173], v[86:87], v[86:87]
	v_add_f32_e32 v152, v166, v167
	v_add_f32_e32 v160, v168, v169
	v_add_f32_e32 v152, v152, v160
	v_add_f32_e32 v160, v170, v171
	v_add_f32_e32 v152, v160, v152
	v_add_f32_e32 v160, v172, v173
	v_add_f32_e32 v248, v160, v152
	s_waitcnt vmcnt(12)
	v_cvt_f32_f16_e32 v166, v214
	v_cvt_f32_f16_sdwa v167, v214 dst_sel:DWORD dst_unused:UNUSED_PAD src0_sel:WORD_1
	v_cvt_f32_f16_e32 v168, v215
	v_cvt_f32_f16_sdwa v169, v215 dst_sel:DWORD dst_unused:UNUSED_PAD src0_sel:WORD_1
	v_cvt_f32_f16_e32 v170, v216
	v_cvt_f32_f16_sdwa v171, v216 dst_sel:DWORD dst_unused:UNUSED_PAD src0_sel:WORD_1
	v_cvt_f32_f16_e32 v172, v217
	v_cvt_f32_f16_sdwa v173, v217 dst_sel:DWORD dst_unused:UNUSED_PAD src0_sel:WORD_1
	v_cvt_f32_f16_e32 v238, v218
	v_cvt_f32_f16_sdwa v239, v218 dst_sel:DWORD dst_unused:UNUSED_PAD src0_sel:WORD_1
	v_cvt_f32_f16_e32 v240, v219
	v_cvt_f32_f16_sdwa v241, v219 dst_sel:DWORD dst_unused:UNUSED_PAD src0_sel:WORD_1
	v_cvt_f32_f16_e32 v242, v220
	v_cvt_f32_f16_sdwa v243, v220 dst_sel:DWORD dst_unused:UNUSED_PAD src0_sel:WORD_1
	v_cvt_f32_f16_e32 v244, v221
	v_cvt_f32_f16_sdwa v245, v221 dst_sel:DWORD dst_unused:UNUSED_PAD src0_sel:WORD_1
	v_pk_fma_f32 v[88:89], v[88:89], v[166:167], v[238:239]
	v_pk_fma_f32 v[90:91], v[90:91], v[168:169], v[240:241]
	v_pk_fma_f32 v[80:81], v[80:81], v[170:171], v[242:243]
	v_pk_fma_f32 v[82:83], v[82:83], v[172:173], v[244:245]
	v_pk_mul_f32 v[166:167], v[88:89], v[88:89]
	v_pk_mul_f32 v[168:169], v[90:91], v[90:91]
	v_pk_mul_f32 v[170:171], v[80:81], v[80:81]
	v_pk_mul_f32 v[172:173], v[82:83], v[82:83]
	v_add_f32_e32 v152, v166, v167
	v_add_f32_e32 v160, v168, v169
	v_add_f32_e32 v152, v152, v160
	v_add_f32_e32 v160, v170, v171
	v_add_f32_e32 v152, v160, v152
	v_add_f32_e32 v160, v172, v173
	v_add_f32_e32 v152, v160, v152
	v_add_f32_e32 v248, v248, v152
	s_mov_b64 exec, s[22:23]
	v_add_u32_e32 v163, 0xa0, v153
	v_cmp_gt_i32_e64 s[18:19], s86, v163
	v_mov_b32_e32 v252, 0
	s_nop 0
	v_cndmask_b32_e64 v143, 0, v163, s[18:19]
	v_lshl_add_u32 v143, v143, 11, v142
	global_load_dwordx4 v[206:209], v143, s[28:29]
	global_load_dwordx4 v[210:213], v143, s[24:25]
	global_load_dwordx4 v[214:217], v143, s[28:29] offset:256
	global_load_dwordx4 v[218:221], v143, s[24:25] offset:256
	s_and_saveexec_b64 s[22:23], s[12:13]
	s_waitcnt vmcnt(14)
	v_cvt_f32_f16_e32 v166, v222
	v_cvt_f32_f16_sdwa v167, v222 dst_sel:DWORD dst_unused:UNUSED_PAD src0_sel:WORD_1
	v_cvt_f32_f16_e32 v168, v223
	v_cvt_f32_f16_sdwa v169, v223 dst_sel:DWORD dst_unused:UNUSED_PAD src0_sel:WORD_1
	v_cvt_f32_f16_e32 v170, v224
	v_cvt_f32_f16_sdwa v171, v224 dst_sel:DWORD dst_unused:UNUSED_PAD src0_sel:WORD_1
	v_cvt_f32_f16_e32 v172, v225
	v_cvt_f32_f16_sdwa v173, v225 dst_sel:DWORD dst_unused:UNUSED_PAD src0_sel:WORD_1
	v_cvt_f32_f16_e32 v238, v226
	v_cvt_f32_f16_sdwa v239, v226 dst_sel:DWORD dst_unused:UNUSED_PAD src0_sel:WORD_1
	v_cvt_f32_f16_e32 v240, v227
	v_cvt_f32_f16_sdwa v241, v227 dst_sel:DWORD dst_unused:UNUSED_PAD src0_sel:WORD_1
	v_cvt_f32_f16_e32 v242, v228
	v_cvt_f32_f16_sdwa v243, v228 dst_sel:DWORD dst_unused:UNUSED_PAD src0_sel:WORD_1
	v_cvt_f32_f16_e32 v244, v229
	v_cvt_f32_f16_sdwa v245, v229 dst_sel:DWORD dst_unused:UNUSED_PAD src0_sel:WORD_1
	v_pk_fma_f32 v[76:77], v[76:77], v[166:167], v[238:239]
	v_pk_fma_f32 v[78:79], v[78:79], v[168:169], v[240:241]
	v_pk_fma_f32 v[68:69], v[68:69], v[170:171], v[242:243]
	v_pk_fma_f32 v[70:71], v[70:71], v[172:173], v[244:245]
	v_pk_mul_f32 v[166:167], v[76:77], v[76:77]
	v_pk_mul_f32 v[168:169], v[78:79], v[78:79]
	v_pk_mul_f32 v[170:171], v[68:69], v[68:69]
	v_pk_mul_f32 v[172:173], v[70:71], v[70:71]
	v_add_f32_e32 v152, v166, v167
	v_add_f32_e32 v160, v168, v169
	v_add_f32_e32 v152, v152, v160
	v_add_f32_e32 v160, v170, v171
	v_add_f32_e32 v152, v160, v152
	v_add_f32_e32 v160, v172, v173
	v_add_f32_e32 v249, v160, v152
	s_waitcnt vmcnt(12)
	v_cvt_f32_f16_e32 v166, v230
	v_cvt_f32_f16_sdwa v167, v230 dst_sel:DWORD dst_unused:UNUSED_PAD src0_sel:WORD_1
	v_cvt_f32_f16_e32 v168, v231
	v_cvt_f32_f16_sdwa v169, v231 dst_sel:DWORD dst_unused:UNUSED_PAD src0_sel:WORD_1
	v_cvt_f32_f16_e32 v170, v232
	v_cvt_f32_f16_sdwa v171, v232 dst_sel:DWORD dst_unused:UNUSED_PAD src0_sel:WORD_1
	v_cvt_f32_f16_e32 v172, v233
	v_cvt_f32_f16_sdwa v173, v233 dst_sel:DWORD dst_unused:UNUSED_PAD src0_sel:WORD_1
	v_cvt_f32_f16_e32 v238, v234
	v_cvt_f32_f16_sdwa v239, v234 dst_sel:DWORD dst_unused:UNUSED_PAD src0_sel:WORD_1
	v_cvt_f32_f16_e32 v240, v235
	v_cvt_f32_f16_sdwa v241, v235 dst_sel:DWORD dst_unused:UNUSED_PAD src0_sel:WORD_1
	v_cvt_f32_f16_e32 v242, v236
	v_cvt_f32_f16_sdwa v243, v236 dst_sel:DWORD dst_unused:UNUSED_PAD src0_sel:WORD_1
	v_cvt_f32_f16_e32 v244, v237
	v_cvt_f32_f16_sdwa v245, v237 dst_sel:DWORD dst_unused:UNUSED_PAD src0_sel:WORD_1
	v_pk_fma_f32 v[72:73], v[72:73], v[166:167], v[238:239]
	v_pk_fma_f32 v[74:75], v[74:75], v[168:169], v[240:241]
	v_pk_fma_f32 v[64:65], v[64:65], v[170:171], v[242:243]
	v_pk_fma_f32 v[66:67], v[66:67], v[172:173], v[244:245]
	v_pk_mul_f32 v[166:167], v[72:73], v[72:73]
	v_pk_mul_f32 v[168:169], v[74:75], v[74:75]
	v_pk_mul_f32 v[170:171], v[64:65], v[64:65]
	v_pk_mul_f32 v[172:173], v[66:67], v[66:67]
	v_add_f32_e32 v152, v166, v167
	v_add_f32_e32 v160, v168, v169
	v_add_f32_e32 v152, v152, v160
	v_add_f32_e32 v160, v170, v171
	v_add_f32_e32 v152, v160, v152
	v_add_f32_e32 v160, v172, v173
	v_add_f32_e32 v152, v160, v152
	v_add_f32_e32 v249, v249, v152
	s_mov_b64 exec, s[22:23]
	v_add_u32_e32 v164, 0xb0, v153
	v_cmp_gt_i32_e64 s[20:21], s86, v164
	v_mov_b32_e32 v253, 0
	s_nop 0
	v_cndmask_b32_e64 v143, 0, v164, s[20:21]
	v_lshl_add_u32 v143, v143, 11, v142
	global_load_dwordx4 v[222:225], v143, s[28:29]
	global_load_dwordx4 v[226:229], v143, s[24:25]
	global_load_dwordx4 v[230:233], v143, s[28:29] offset:256
	global_load_dwordx4 v[234:237], v143, s[24:25] offset:256
	s_and_saveexec_b64 s[22:23], s[14:15]
	s_waitcnt vmcnt(14)
	v_cvt_f32_f16_e32 v166, v174
	v_cvt_f32_f16_sdwa v167, v174 dst_sel:DWORD dst_unused:UNUSED_PAD src0_sel:WORD_1
	v_cvt_f32_f16_e32 v168, v175
	v_cvt_f32_f16_sdwa v169, v175 dst_sel:DWORD dst_unused:UNUSED_PAD src0_sel:WORD_1
	v_cvt_f32_f16_e32 v170, v176
	v_cvt_f32_f16_sdwa v171, v176 dst_sel:DWORD dst_unused:UNUSED_PAD src0_sel:WORD_1
	v_cvt_f32_f16_e32 v172, v177
	v_cvt_f32_f16_sdwa v173, v177 dst_sel:DWORD dst_unused:UNUSED_PAD src0_sel:WORD_1
	v_cvt_f32_f16_e32 v238, v178
	v_cvt_f32_f16_sdwa v239, v178 dst_sel:DWORD dst_unused:UNUSED_PAD src0_sel:WORD_1
	v_cvt_f32_f16_e32 v240, v179
	v_cvt_f32_f16_sdwa v241, v179 dst_sel:DWORD dst_unused:UNUSED_PAD src0_sel:WORD_1
	v_cvt_f32_f16_e32 v242, v180
	v_cvt_f32_f16_sdwa v243, v180 dst_sel:DWORD dst_unused:UNUSED_PAD src0_sel:WORD_1
	v_cvt_f32_f16_e32 v244, v181
	v_cvt_f32_f16_sdwa v245, v181 dst_sel:DWORD dst_unused:UNUSED_PAD src0_sel:WORD_1
	v_pk_fma_f32 v[60:61], v[60:61], v[166:167], v[238:239]
	v_pk_fma_f32 v[62:63], v[62:63], v[168:169], v[240:241]
	v_pk_fma_f32 v[52:53], v[52:53], v[170:171], v[242:243]
	v_pk_fma_f32 v[54:55], v[54:55], v[172:173], v[244:245]
	v_pk_mul_f32 v[166:167], v[60:61], v[60:61]
	v_pk_mul_f32 v[168:169], v[62:63], v[62:63]
	v_pk_mul_f32 v[170:171], v[52:53], v[52:53]
	v_pk_mul_f32 v[172:173], v[54:55], v[54:55]
	v_add_f32_e32 v152, v166, v167
	v_add_f32_e32 v160, v168, v169
	v_add_f32_e32 v152, v152, v160
	v_add_f32_e32 v160, v170, v171
	v_add_f32_e32 v152, v160, v152
	v_add_f32_e32 v160, v172, v173
	v_add_f32_e32 v250, v160, v152
	s_waitcnt vmcnt(12)
	v_cvt_f32_f16_e32 v166, v182
	v_cvt_f32_f16_sdwa v167, v182 dst_sel:DWORD dst_unused:UNUSED_PAD src0_sel:WORD_1
	v_cvt_f32_f16_e32 v168, v183
	v_cvt_f32_f16_sdwa v169, v183 dst_sel:DWORD dst_unused:UNUSED_PAD src0_sel:WORD_1
	v_cvt_f32_f16_e32 v170, v184
	v_cvt_f32_f16_sdwa v171, v184 dst_sel:DWORD dst_unused:UNUSED_PAD src0_sel:WORD_1
	v_cvt_f32_f16_e32 v172, v185
	v_cvt_f32_f16_sdwa v173, v185 dst_sel:DWORD dst_unused:UNUSED_PAD src0_sel:WORD_1
	v_cvt_f32_f16_e32 v238, v186
	v_cvt_f32_f16_sdwa v239, v186 dst_sel:DWORD dst_unused:UNUSED_PAD src0_sel:WORD_1
	v_cvt_f32_f16_e32 v240, v187
	v_cvt_f32_f16_sdwa v241, v187 dst_sel:DWORD dst_unused:UNUSED_PAD src0_sel:WORD_1
	v_cvt_f32_f16_e32 v242, v188
	v_cvt_f32_f16_sdwa v243, v188 dst_sel:DWORD dst_unused:UNUSED_PAD src0_sel:WORD_1
	v_cvt_f32_f16_e32 v244, v189
	v_cvt_f32_f16_sdwa v245, v189 dst_sel:DWORD dst_unused:UNUSED_PAD src0_sel:WORD_1
	v_pk_fma_f32 v[56:57], v[56:57], v[166:167], v[238:239]
	v_pk_fma_f32 v[58:59], v[58:59], v[168:169], v[240:241]
	v_pk_fma_f32 v[48:49], v[48:49], v[170:171], v[242:243]
	v_pk_fma_f32 v[50:51], v[50:51], v[172:173], v[244:245]
	v_pk_mul_f32 v[166:167], v[56:57], v[56:57]
	v_pk_mul_f32 v[168:169], v[58:59], v[58:59]
	v_pk_mul_f32 v[170:171], v[48:49], v[48:49]
	v_pk_mul_f32 v[172:173], v[50:51], v[50:51]
	v_add_f32_e32 v152, v166, v167
	v_add_f32_e32 v160, v168, v169
	v_add_f32_e32 v152, v152, v160
	v_add_f32_e32 v160, v170, v171
	v_add_f32_e32 v152, v160, v152
	v_add_f32_e32 v160, v172, v173
	v_add_f32_e32 v152, v160, v152
	v_add_f32_e32 v250, v250, v152
	s_mov_b64 exec, s[22:23]
	v_lshl_add_u32 v143, v154, 3, s70
	v_lshl_add_u32 v143, s30, 8, v143
	v_lshlrev_b32_e32 v143, 2, v143
	global_load_dwordx4 v[174:177], v143, s[92:93]
	global_load_dwordx4 v[178:181], v143, s[92:93] offset:16
	global_load_dwordx4 v[182:185], v143, s[92:93] offset:512
	global_load_dwordx4 v[186:189], v143, s[92:93] offset:528
	s_and_saveexec_b64 s[22:23], s[16:17]
	s_waitcnt vmcnt(14)
	v_cvt_f32_f16_e32 v166, v190
	v_cvt_f32_f16_sdwa v167, v190 dst_sel:DWORD dst_unused:UNUSED_PAD src0_sel:WORD_1
	v_cvt_f32_f16_e32 v168, v191
	v_cvt_f32_f16_sdwa v169, v191 dst_sel:DWORD dst_unused:UNUSED_PAD src0_sel:WORD_1
	v_cvt_f32_f16_e32 v170, v192
	v_cvt_f32_f16_sdwa v171, v192 dst_sel:DWORD dst_unused:UNUSED_PAD src0_sel:WORD_1
	v_cvt_f32_f16_e32 v172, v193
	v_cvt_f32_f16_sdwa v173, v193 dst_sel:DWORD dst_unused:UNUSED_PAD src0_sel:WORD_1
	v_cvt_f32_f16_e32 v238, v194
	v_cvt_f32_f16_sdwa v239, v194 dst_sel:DWORD dst_unused:UNUSED_PAD src0_sel:WORD_1
	v_cvt_f32_f16_e32 v240, v195
	v_cvt_f32_f16_sdwa v241, v195 dst_sel:DWORD dst_unused:UNUSED_PAD src0_sel:WORD_1
	v_cvt_f32_f16_e32 v242, v196
	v_cvt_f32_f16_sdwa v243, v196 dst_sel:DWORD dst_unused:UNUSED_PAD src0_sel:WORD_1
	v_cvt_f32_f16_e32 v244, v197
	v_cvt_f32_f16_sdwa v245, v197 dst_sel:DWORD dst_unused:UNUSED_PAD src0_sel:WORD_1
	v_pk_fma_f32 v[44:45], v[44:45], v[166:167], v[238:239]
	v_pk_fma_f32 v[46:47], v[46:47], v[168:169], v[240:241]
	v_pk_fma_f32 v[36:37], v[36:37], v[170:171], v[242:243]
	v_pk_fma_f32 v[38:39], v[38:39], v[172:173], v[244:245]
	v_pk_mul_f32 v[166:167], v[44:45], v[44:45]
	v_pk_mul_f32 v[168:169], v[46:47], v[46:47]
	v_pk_mul_f32 v[170:171], v[36:37], v[36:37]
	v_pk_mul_f32 v[172:173], v[38:39], v[38:39]
	v_add_f32_e32 v152, v166, v167
	v_add_f32_e32 v160, v168, v169
	v_add_f32_e32 v152, v152, v160
	v_add_f32_e32 v160, v170, v171
	v_add_f32_e32 v152, v160, v152
	v_add_f32_e32 v160, v172, v173
	v_add_f32_e32 v251, v160, v152
	s_waitcnt vmcnt(12)
	v_cvt_f32_f16_e32 v166, v198
	v_cvt_f32_f16_sdwa v167, v198 dst_sel:DWORD dst_unused:UNUSED_PAD src0_sel:WORD_1
	v_cvt_f32_f16_e32 v168, v199
	v_cvt_f32_f16_sdwa v169, v199 dst_sel:DWORD dst_unused:UNUSED_PAD src0_sel:WORD_1
	v_cvt_f32_f16_e32 v170, v200
	v_cvt_f32_f16_sdwa v171, v200 dst_sel:DWORD dst_unused:UNUSED_PAD src0_sel:WORD_1
	v_cvt_f32_f16_e32 v172, v201
	v_cvt_f32_f16_sdwa v173, v201 dst_sel:DWORD dst_unused:UNUSED_PAD src0_sel:WORD_1
	v_cvt_f32_f16_e32 v238, v202
	v_cvt_f32_f16_sdwa v239, v202 dst_sel:DWORD dst_unused:UNUSED_PAD src0_sel:WORD_1
	v_cvt_f32_f16_e32 v240, v203
	v_cvt_f32_f16_sdwa v241, v203 dst_sel:DWORD dst_unused:UNUSED_PAD src0_sel:WORD_1
	v_cvt_f32_f16_e32 v242, v204
	v_cvt_f32_f16_sdwa v243, v204 dst_sel:DWORD dst_unused:UNUSED_PAD src0_sel:WORD_1
	v_cvt_f32_f16_e32 v244, v205
	v_cvt_f32_f16_sdwa v245, v205 dst_sel:DWORD dst_unused:UNUSED_PAD src0_sel:WORD_1
	v_pk_fma_f32 v[40:41], v[40:41], v[166:167], v[238:239]
	v_pk_fma_f32 v[42:43], v[42:43], v[168:169], v[240:241]
	v_pk_fma_f32 v[32:33], v[32:33], v[170:171], v[242:243]
	v_pk_fma_f32 v[34:35], v[34:35], v[172:173], v[244:245]
	v_pk_mul_f32 v[166:167], v[40:41], v[40:41]
	v_pk_mul_f32 v[168:169], v[42:43], v[42:43]
	v_pk_mul_f32 v[170:171], v[32:33], v[32:33]
	v_pk_mul_f32 v[172:173], v[34:35], v[34:35]
	v_add_f32_e32 v152, v166, v167
	v_add_f32_e32 v160, v168, v169
	v_add_f32_e32 v152, v152, v160
	v_add_f32_e32 v160, v170, v171
	v_add_f32_e32 v152, v160, v152
	v_add_f32_e32 v160, v172, v173
	v_add_f32_e32 v152, v160, v152
	v_add_f32_e32 v251, v251, v152
	s_mov_b64 exec, s[22:23]
	s_and_saveexec_b64 s[22:23], s[18:19]
	s_waitcnt vmcnt(10)
	v_cvt_f32_f16_e32 v166, v206
	v_cvt_f32_f16_sdwa v167, v206 dst_sel:DWORD dst_unused:UNUSED_PAD src0_sel:WORD_1
	v_cvt_f32_f16_e32 v168, v207
	v_cvt_f32_f16_sdwa v169, v207 dst_sel:DWORD dst_unused:UNUSED_PAD src0_sel:WORD_1
	v_cvt_f32_f16_e32 v170, v208
	v_cvt_f32_f16_sdwa v171, v208 dst_sel:DWORD dst_unused:UNUSED_PAD src0_sel:WORD_1
	v_cvt_f32_f16_e32 v172, v209
	v_cvt_f32_f16_sdwa v173, v209 dst_sel:DWORD dst_unused:UNUSED_PAD src0_sel:WORD_1
	v_cvt_f32_f16_e32 v238, v210
	v_cvt_f32_f16_sdwa v239, v210 dst_sel:DWORD dst_unused:UNUSED_PAD src0_sel:WORD_1
	v_cvt_f32_f16_e32 v240, v211
	v_cvt_f32_f16_sdwa v241, v211 dst_sel:DWORD dst_unused:UNUSED_PAD src0_sel:WORD_1
	v_cvt_f32_f16_e32 v242, v212
	v_cvt_f32_f16_sdwa v243, v212 dst_sel:DWORD dst_unused:UNUSED_PAD src0_sel:WORD_1
	v_cvt_f32_f16_e32 v244, v213
	v_cvt_f32_f16_sdwa v245, v213 dst_sel:DWORD dst_unused:UNUSED_PAD src0_sel:WORD_1
	v_pk_fma_f32 v[28:29], v[28:29], v[166:167], v[238:239]
	v_pk_fma_f32 v[30:31], v[30:31], v[168:169], v[240:241]
	v_pk_fma_f32 v[20:21], v[20:21], v[170:171], v[242:243]
	v_pk_fma_f32 v[22:23], v[22:23], v[172:173], v[244:245]
	v_pk_mul_f32 v[166:167], v[28:29], v[28:29]
	v_pk_mul_f32 v[168:169], v[30:31], v[30:31]
	v_pk_mul_f32 v[170:171], v[20:21], v[20:21]
	v_pk_mul_f32 v[172:173], v[22:23], v[22:23]
	v_add_f32_e32 v152, v166, v167
	v_add_f32_e32 v160, v168, v169
	v_add_f32_e32 v152, v152, v160
	v_add_f32_e32 v160, v170, v171
	v_add_f32_e32 v152, v160, v152
	v_add_f32_e32 v160, v172, v173
	v_add_f32_e32 v252, v160, v152
	s_waitcnt vmcnt(8)
	v_cvt_f32_f16_e32 v166, v214
	v_cvt_f32_f16_sdwa v167, v214 dst_sel:DWORD dst_unused:UNUSED_PAD src0_sel:WORD_1
	v_cvt_f32_f16_e32 v168, v215
	v_cvt_f32_f16_sdwa v169, v215 dst_sel:DWORD dst_unused:UNUSED_PAD src0_sel:WORD_1
	v_cvt_f32_f16_e32 v170, v216
	v_cvt_f32_f16_sdwa v171, v216 dst_sel:DWORD dst_unused:UNUSED_PAD src0_sel:WORD_1
	v_cvt_f32_f16_e32 v172, v217
	v_cvt_f32_f16_sdwa v173, v217 dst_sel:DWORD dst_unused:UNUSED_PAD src0_sel:WORD_1
	v_cvt_f32_f16_e32 v238, v218
	v_cvt_f32_f16_sdwa v239, v218 dst_sel:DWORD dst_unused:UNUSED_PAD src0_sel:WORD_1
	v_cvt_f32_f16_e32 v240, v219
	v_cvt_f32_f16_sdwa v241, v219 dst_sel:DWORD dst_unused:UNUSED_PAD src0_sel:WORD_1
	v_cvt_f32_f16_e32 v242, v220
	v_cvt_f32_f16_sdwa v243, v220 dst_sel:DWORD dst_unused:UNUSED_PAD src0_sel:WORD_1
	v_cvt_f32_f16_e32 v244, v221
	v_cvt_f32_f16_sdwa v245, v221 dst_sel:DWORD dst_unused:UNUSED_PAD src0_sel:WORD_1
	v_pk_fma_f32 v[24:25], v[24:25], v[166:167], v[238:239]
	v_pk_fma_f32 v[26:27], v[26:27], v[168:169], v[240:241]
	v_pk_fma_f32 v[16:17], v[16:17], v[170:171], v[242:243]
	v_pk_fma_f32 v[18:19], v[18:19], v[172:173], v[244:245]
	v_pk_mul_f32 v[166:167], v[24:25], v[24:25]
	v_pk_mul_f32 v[168:169], v[26:27], v[26:27]
	v_pk_mul_f32 v[170:171], v[16:17], v[16:17]
	v_pk_mul_f32 v[172:173], v[18:19], v[18:19]
	v_add_f32_e32 v152, v166, v167
	v_add_f32_e32 v160, v168, v169
	v_add_f32_e32 v152, v152, v160
	v_add_f32_e32 v160, v170, v171
	v_add_f32_e32 v152, v160, v152
	v_add_f32_e32 v160, v172, v173
	v_add_f32_e32 v152, v160, v152
	v_add_f32_e32 v252, v252, v152
	s_mov_b64 exec, s[22:23]
	s_and_saveexec_b64 s[22:23], s[20:21]
	s_waitcnt vmcnt(6)
	v_cvt_f32_f16_e32 v166, v222
	v_cvt_f32_f16_sdwa v167, v222 dst_sel:DWORD dst_unused:UNUSED_PAD src0_sel:WORD_1
	v_cvt_f32_f16_e32 v168, v223
	v_cvt_f32_f16_sdwa v169, v223 dst_sel:DWORD dst_unused:UNUSED_PAD src0_sel:WORD_1
	v_cvt_f32_f16_e32 v170, v224
	v_cvt_f32_f16_sdwa v171, v224 dst_sel:DWORD dst_unused:UNUSED_PAD src0_sel:WORD_1
	v_cvt_f32_f16_e32 v172, v225
	v_cvt_f32_f16_sdwa v173, v225 dst_sel:DWORD dst_unused:UNUSED_PAD src0_sel:WORD_1
	v_cvt_f32_f16_e32 v238, v226
	v_cvt_f32_f16_sdwa v239, v226 dst_sel:DWORD dst_unused:UNUSED_PAD src0_sel:WORD_1
	v_cvt_f32_f16_e32 v240, v227
	v_cvt_f32_f16_sdwa v241, v227 dst_sel:DWORD dst_unused:UNUSED_PAD src0_sel:WORD_1
	v_cvt_f32_f16_e32 v242, v228
	v_cvt_f32_f16_sdwa v243, v228 dst_sel:DWORD dst_unused:UNUSED_PAD src0_sel:WORD_1
	v_cvt_f32_f16_e32 v244, v229
	v_cvt_f32_f16_sdwa v245, v229 dst_sel:DWORD dst_unused:UNUSED_PAD src0_sel:WORD_1
	v_pk_fma_f32 v[12:13], v[12:13], v[166:167], v[238:239]
	v_pk_fma_f32 v[14:15], v[14:15], v[168:169], v[240:241]
	v_pk_fma_f32 v[4:5], v[4:5], v[170:171], v[242:243]
	v_pk_fma_f32 v[6:7], v[6:7], v[172:173], v[244:245]
	v_pk_mul_f32 v[166:167], v[12:13], v[12:13]
	v_pk_mul_f32 v[168:169], v[14:15], v[14:15]
	v_pk_mul_f32 v[170:171], v[4:5], v[4:5]
	v_pk_mul_f32 v[172:173], v[6:7], v[6:7]
	v_add_f32_e32 v152, v166, v167
	v_add_f32_e32 v160, v168, v169
	v_add_f32_e32 v152, v152, v160
	v_add_f32_e32 v160, v170, v171
	v_add_f32_e32 v152, v160, v152
	v_add_f32_e32 v160, v172, v173
	v_add_f32_e32 v253, v160, v152
	s_waitcnt vmcnt(4)
	v_cvt_f32_f16_e32 v166, v230
	v_cvt_f32_f16_sdwa v167, v230 dst_sel:DWORD dst_unused:UNUSED_PAD src0_sel:WORD_1
	v_cvt_f32_f16_e32 v168, v231
	v_cvt_f32_f16_sdwa v169, v231 dst_sel:DWORD dst_unused:UNUSED_PAD src0_sel:WORD_1
	v_cvt_f32_f16_e32 v170, v232
	v_cvt_f32_f16_sdwa v171, v232 dst_sel:DWORD dst_unused:UNUSED_PAD src0_sel:WORD_1
	v_cvt_f32_f16_e32 v172, v233
	v_cvt_f32_f16_sdwa v173, v233 dst_sel:DWORD dst_unused:UNUSED_PAD src0_sel:WORD_1
	v_cvt_f32_f16_e32 v238, v234
	v_cvt_f32_f16_sdwa v239, v234 dst_sel:DWORD dst_unused:UNUSED_PAD src0_sel:WORD_1
	v_cvt_f32_f16_e32 v240, v235
	v_cvt_f32_f16_sdwa v241, v235 dst_sel:DWORD dst_unused:UNUSED_PAD src0_sel:WORD_1
	v_cvt_f32_f16_e32 v242, v236
	v_cvt_f32_f16_sdwa v243, v236 dst_sel:DWORD dst_unused:UNUSED_PAD src0_sel:WORD_1
	v_cvt_f32_f16_e32 v244, v237
	v_cvt_f32_f16_sdwa v245, v237 dst_sel:DWORD dst_unused:UNUSED_PAD src0_sel:WORD_1
	v_pk_fma_f32 v[8:9], v[8:9], v[166:167], v[238:239]
	v_pk_fma_f32 v[10:11], v[10:11], v[168:169], v[240:241]
	v_pk_fma_f32 v[0:1], v[0:1], v[170:171], v[242:243]
	v_pk_fma_f32 v[2:3], v[2:3], v[172:173], v[244:245]
	v_pk_mul_f32 v[166:167], v[8:9], v[8:9]
	v_pk_mul_f32 v[168:169], v[10:11], v[10:11]
	v_pk_mul_f32 v[170:171], v[0:1], v[0:1]
	v_pk_mul_f32 v[172:173], v[2:3], v[2:3]
	v_add_f32_e32 v152, v166, v167
	v_add_f32_e32 v160, v168, v169
	v_add_f32_e32 v152, v152, v160
	v_add_f32_e32 v160, v170, v171
	v_add_f32_e32 v152, v160, v152
	v_add_f32_e32 v160, v172, v173
	v_add_f32_e32 v152, v160, v152
	v_add_f32_e32 v253, v253, v152
	s_mov_b64 exec, s[22:23]
	v_and_b32_e32 v152, 64, v151
	v_xor_b32_e32 v143, 16, v151
	v_add_u32_e32 v152, 64, v152
	v_xor_b32_e32 v160, 32, v151
	v_cmp_lt_i32_e32 vcc, v143, v152
	s_nop 1
	v_cndmask_b32_e32 v143, v151, v143, vcc
	v_lshlrev_b32_e32 v143, 2, v143
	v_cmp_lt_i32_e32 vcc, v160, v152
	s_nop 1
	v_cndmask_b32_e32 v152, v151, v160, vcc
	v_lshlrev_b32_e32 v160, 2, v152
	v_cmp_eq_u32_e32 vcc, 0, v154
	ds_bpermute_b32 v166, v143, v246
	ds_bpermute_b32 v167, v143, v247
	ds_bpermute_b32 v168, v143, v248
	ds_bpermute_b32 v169, v143, v249
	ds_bpermute_b32 v170, v143, v250
	ds_bpermute_b32 v171, v143, v251
	ds_bpermute_b32 v172, v143, v252
	ds_bpermute_b32 v173, v143, v253
	s_waitcnt lgkmcnt(7)
	v_add_f32_e32 v246, v246, v166
	s_waitcnt lgkmcnt(6)
	v_add_f32_e32 v247, v247, v167
	s_waitcnt lgkmcnt(5)
	v_add_f32_e32 v248, v248, v168
	s_waitcnt lgkmcnt(4)
	v_add_f32_e32 v249, v249, v169
	s_waitcnt lgkmcnt(3)
	v_add_f32_e32 v250, v250, v170
	s_waitcnt lgkmcnt(2)
	v_add_f32_e32 v251, v251, v171
	s_waitcnt lgkmcnt(1)
	v_add_f32_e32 v252, v252, v172
	s_waitcnt lgkmcnt(0)
	v_add_f32_e32 v253, v253, v173
	s_nop 0
	ds_bpermute_b32 v166, v160, v246
	ds_bpermute_b32 v167, v160, v247
	ds_bpermute_b32 v168, v160, v248
	ds_bpermute_b32 v169, v160, v249
	ds_bpermute_b32 v170, v160, v250
	ds_bpermute_b32 v171, v160, v251
	ds_bpermute_b32 v172, v160, v252
	ds_bpermute_b32 v173, v160, v253
	s_and_saveexec_b64 s[22:23], vcc
	s_waitcnt lgkmcnt(7)
	v_add_f32_e32 v166, v246, v166
	s_waitcnt lgkmcnt(6)
	v_add_f32_e32 v167, v247, v167
	s_waitcnt lgkmcnt(5)
	v_add_f32_e32 v168, v248, v168
	s_waitcnt lgkmcnt(4)
	v_add_f32_e32 v169, v249, v169
	s_waitcnt lgkmcnt(3)
	v_add_f32_e32 v170, v250, v170
	s_waitcnt lgkmcnt(2)
	v_add_f32_e32 v171, v251, v171
	s_waitcnt lgkmcnt(1)
	v_add_f32_e32 v172, v252, v172
	s_waitcnt lgkmcnt(0)
	v_add_f32_e32 v173, v253, v173
	ds_write_b32 v161, v166
	ds_write_b32 v161, v167 offset:256
	ds_write_b32 v161, v168 offset:512
	ds_write_b32 v161, v169 offset:768
	ds_write_b32 v161, v170 offset:2048
	ds_write_b32 v161, v171 offset:2304
	ds_write_b32 v161, v172 offset:2560
	ds_write_b32 v161, v173 offset:2816
	s_mov_b64 exec, s[22:23]
	s_ashr_i32 s51, s50, 31
	s_lshl_b64 s[22:23], s[50:51], 12
	v_add_u32_e32 v160, v136, v155
	s_waitcnt lgkmcnt(0)
	s_barrier
	s_add_u32 s22, s80, s22
	v_and_or_b32 v136, v160, 31, s71
	s_addc_u32 s23, s81, s23
	s_waitcnt lgkmcnt(0)
	v_lshl_add_u64 v[142:143], v[136:137], 4, s[22:23]
	v_cmp_gt_i32_e64 s[22:23], 32, v160
	s_and_saveexec_b64 s[52:53], s[22:23]
	s_cbranch_execz .LBB0_1521
	v_lshl_add_u32 v152, v136, 4, 0
	v_add_u32_e32 v152, 0x20000, v152
	ds_read_b128 v[166:169], v152
	s_ashr_i32 s31, s30, 31
	v_lshl_add_u64 v[170:171], s[30:31], 2, v[142:143]
	s_waitcnt lgkmcnt(0)
	v_mov_b32_e32 v172, v167
	v_mov_b32_e32 v173, v168
	v_mov_b32_e32 v167, v169
	v_pk_add_f32 v[166:167], v[172:173], v[166:167]
	s_nop 0
	v_pk_add_f32 v[166:167], v[166:167], v[166:167] op_sel:[0,1] op_sel_hi:[1,0]
	global_store_dword v[170:171], v166, off sc1

.LBB0_1536:
	s_or_b64 exec, exec, s[50:51]
	s_waitcnt vmcnt(0) lgkmcnt(0)
	s_barrier
	v_lshl_add_u32 v136, v155, 2, s79
	v_lshl_add_u32 v142, v154, 3, s70
	v_readlane_b32 s88, v255, 0
	v_readlane_b32 s89, v255, 1
	v_readlane_b32 s90, v255, 2
	v_readlane_b32 s91, v255, 3
	v_readlane_b32 s92, v255, 4
	v_readlane_b32 s93, v255, 5
	v_readlane_b32 s94, v255, 6
	v_readlane_b32 s95, v255, 7
	ds_read_b32 v190, v136
	ds_read_b32 v192, v136 offset:64
	ds_read_b32 v194, v136 offset:128
	ds_read_b32 v196, v136 offset:192
	ds_read_b32 v198, v136 offset:512
	ds_read_b32 v200, v136 offset:576
	ds_read_b32 v202, v136 offset:640
	ds_read_b32 v204, v136 offset:704
	v_lshl_add_u32 v154, s30, 8, v142
	s_waitcnt lgkmcnt(7)
	s_and_saveexec_b64 s[22:23], s[6:7]
	v_pk_mul_f32 v[126:127], v[126:127], v[190:191] op_sel_hi:[1,0]
	v_pk_mul_f32 v[124:125], v[124:125], v[190:191] op_sel_hi:[1,0]
	v_pk_mul_f32 v[118:119], v[118:119], v[190:191] op_sel_hi:[1,0]
	v_pk_mul_f32 v[116:117], v[116:117], v[190:191] op_sel_hi:[1,0]
	v_pk_mul_f32 v[122:123], v[122:123], v[190:191] op_sel_hi:[1,0]
	v_pk_mul_f32 v[120:121], v[120:121], v[190:191] op_sel_hi:[1,0]
	v_pk_mul_f32 v[114:115], v[114:115], v[190:191] op_sel_hi:[1,0]
	v_pk_mul_f32 v[112:113], v[112:113], v[190:191] op_sel_hi:[1,0]
	v_lshlrev_b32_e32 v143, 12, v153
	v_lshl_add_u32 v152, v154, 2, v143
	v_pk_mul_f32 v[124:125], v[174:175], v[124:125]
	v_pk_mul_f32 v[126:127], v[176:177], v[126:127]
	v_pk_mul_f32 v[116:117], v[178:179], v[116:117]
	v_pk_mul_f32 v[118:119], v[180:181], v[118:119]
	v_pk_mul_f32 v[120:121], v[182:183], v[120:121]
	v_pk_mul_f32 v[122:123], v[184:185], v[122:123]
	v_pk_mul_f32 v[112:113], v[186:187], v[112:113]
	v_pk_mul_f32 v[114:115], v[188:189], v[114:115]
	global_store_dwordx4 v152, v[124:127], s[94:95]
	global_store_dwordx4 v152, v[116:119], s[94:95] offset:16
	global_store_dwordx4 v152, v[120:123], s[94:95] offset:512
	global_store_dwordx4 v152, v[112:115], s[94:95] offset:528
	s_mov_b64 exec, s[22:23]
	s_waitcnt lgkmcnt(6)
	s_and_saveexec_b64 s[22:23], s[8:9]
	v_pk_mul_f32 v[110:111], v[110:111], v[192:193] op_sel_hi:[1,0]
	v_pk_mul_f32 v[108:109], v[108:109], v[192:193] op_sel_hi:[1,0]
	v_pk_mul_f32 v[102:103], v[102:103], v[192:193] op_sel_hi:[1,0]
	v_pk_mul_f32 v[100:101], v[100:101], v[192:193] op_sel_hi:[1,0]
	v_pk_mul_f32 v[106:107], v[106:107], v[192:193] op_sel_hi:[1,0]
	v_pk_mul_f32 v[104:105], v[104:105], v[192:193] op_sel_hi:[1,0]
	v_pk_mul_f32 v[98:99], v[98:99], v[192:193] op_sel_hi:[1,0]
	v_pk_mul_f32 v[96:97], v[96:97], v[192:193] op_sel_hi:[1,0]
	v_lshlrev_b32_e32 v143, 12, v156
	v_lshl_add_u32 v152, v154, 2, v143
	v_pk_mul_f32 v[108:109], v[174:175], v[108:109]
	v_pk_mul_f32 v[110:111], v[176:177], v[110:111]
	v_pk_mul_f32 v[100:101], v[178:179], v[100:101]
	v_pk_mul_f32 v[102:103], v[180:181], v[102:103]
	v_pk_mul_f32 v[104:105], v[182:183], v[104:105]
	v_pk_mul_f32 v[106:107], v[184:185], v[106:107]
	v_pk_mul_f32 v[96:97], v[186:187], v[96:97]
	v_pk_mul_f32 v[98:99], v[188:189], v[98:99]
	global_store_dwordx4 v152, v[108:111], s[94:95]
	global_store_dwordx4 v152, v[100:103], s[94:95] offset:16
	global_store_dwordx4 v152, v[104:107], s[94:95] offset:512
	global_store_dwordx4 v152, v[96:99], s[94:95] offset:528
	s_mov_b64 exec, s[22:23]
	s_waitcnt lgkmcnt(5)
	s_and_saveexec_b64 s[22:23], s[10:11]
	v_pk_mul_f32 v[94:95], v[94:95], v[194:195] op_sel_hi:[1,0]
	v_pk_mul_f32 v[92:93], v[92:93], v[194:195] op_sel_hi:[1,0]
	v_pk_mul_f32 v[86:87], v[86:87], v[194:195] op_sel_hi:[1,0]
	v_pk_mul_f32 v[84:85], v[84:85], v[194:195] op_sel_hi:[1,0]
	v_pk_mul_f32 v[90:91], v[90:91], v[194:195] op_sel_hi:[1,0]
	v_pk_mul_f32 v[88:89], v[88:89], v[194:195] op_sel_hi:[1,0]
	v_pk_mul_f32 v[82:83], v[82:83], v[194:195] op_sel_hi:[1,0]
	v_pk_mul_f32 v[80:81], v[80:81], v[194:195] op_sel_hi:[1,0]
	v_lshlrev_b32_e32 v143, 12, v157
	v_lshl_add_u32 v152, v154, 2, v143
	v_pk_mul_f32 v[92:93], v[174:175], v[92:93]
	v_pk_mul_f32 v[94:95], v[176:177], v[94:95]
	v_pk_mul_f32 v[84:85], v[178:179], v[84:85]
	v_pk_mul_f32 v[86:87], v[180:181], v[86:87]
	v_pk_mul_f32 v[88:89], v[182:183], v[88:89]
	v_pk_mul_f32 v[90:91], v[184:185], v[90:91]
	v_pk_mul_f32 v[80:81], v[186:187], v[80:81]
	v_pk_mul_f32 v[82:83], v[188:189], v[82:83]
	global_store_dwordx4 v152, v[92:95], s[94:95]
	global_store_dwordx4 v152, v[84:87], s[94:95] offset:16
	global_store_dwordx4 v152, v[88:91], s[94:95] offset:512
	global_store_dwordx4 v152, v[80:83], s[94:95] offset:528
	s_mov_b64 exec, s[22:23]
	s_waitcnt lgkmcnt(4)
	s_and_saveexec_b64 s[22:23], s[12:13]
	v_pk_mul_f32 v[78:79], v[78:79], v[196:197] op_sel_hi:[1,0]
	v_pk_mul_f32 v[76:77], v[76:77], v[196:197] op_sel_hi:[1,0]
	v_pk_mul_f32 v[70:71], v[70:71], v[196:197] op_sel_hi:[1,0]
	v_pk_mul_f32 v[68:69], v[68:69], v[196:197] op_sel_hi:[1,0]
	v_pk_mul_f32 v[74:75], v[74:75], v[196:197] op_sel_hi:[1,0]
	v_pk_mul_f32 v[72:73], v[72:73], v[196:197] op_sel_hi:[1,0]
	v_pk_mul_f32 v[66:67], v[66:67], v[196:197] op_sel_hi:[1,0]
	v_pk_mul_f32 v[64:65], v[64:65], v[196:197] op_sel_hi:[1,0]
	v_lshlrev_b32_e32 v143, 12, v158
	v_lshl_add_u32 v152, v154, 2, v143
	v_pk_mul_f32 v[76:77], v[174:175], v[76:77]
	v_pk_mul_f32 v[78:79], v[176:177], v[78:79]
	v_pk_mul_f32 v[68:69], v[178:179], v[68:69]
	v_pk_mul_f32 v[70:71], v[180:181], v[70:71]
	v_pk_mul_f32 v[72:73], v[182:183], v[72:73]
	v_pk_mul_f32 v[74:75], v[184:185], v[74:75]
	v_pk_mul_f32 v[64:65], v[186:187], v[64:65]
	v_pk_mul_f32 v[66:67], v[188:189], v[66:67]
	global_store_dwordx4 v152, v[76:79], s[94:95]
	global_store_dwordx4 v152, v[68:71], s[94:95] offset:16
	global_store_dwordx4 v152, v[72:75], s[94:95] offset:512
	global_store_dwordx4 v152, v[64:67], s[94:95] offset:528
	s_mov_b64 exec, s[22:23]
	s_waitcnt lgkmcnt(3)
	s_and_saveexec_b64 s[22:23], s[14:15]
	v_pk_mul_f32 v[62:63], v[62:63], v[198:199] op_sel_hi:[1,0]
	v_pk_mul_f32 v[60:61], v[60:61], v[198:199] op_sel_hi:[1,0]
	v_pk_mul_f32 v[54:55], v[54:55], v[198:199] op_sel_hi:[1,0]
	v_pk_mul_f32 v[52:53], v[52:53], v[198:199] op_sel_hi:[1,0]
	v_pk_mul_f32 v[58:59], v[58:59], v[198:199] op_sel_hi:[1,0]
	v_pk_mul_f32 v[56:57], v[56:57], v[198:199] op_sel_hi:[1,0]
	v_pk_mul_f32 v[50:51], v[50:51], v[198:199] op_sel_hi:[1,0]
	v_pk_mul_f32 v[48:49], v[48:49], v[198:199] op_sel_hi:[1,0]
	v_lshlrev_b32_e32 v143, 12, v159
	v_lshl_add_u32 v152, v154, 2, v143
	v_pk_mul_f32 v[60:61], v[174:175], v[60:61]
	v_pk_mul_f32 v[62:63], v[176:177], v[62:63]
	v_pk_mul_f32 v[52:53], v[178:179], v[52:53]
	v_pk_mul_f32 v[54:55], v[180:181], v[54:55]
	v_pk_mul_f32 v[56:57], v[182:183], v[56:57]
	v_pk_mul_f32 v[58:59], v[184:185], v[58:59]
	v_pk_mul_f32 v[48:49], v[186:187], v[48:49]
	v_pk_mul_f32 v[50:51], v[188:189], v[50:51]
	global_store_dwordx4 v152, v[60:63], s[94:95]
	global_store_dwordx4 v152, v[52:55], s[94:95] offset:16
	global_store_dwordx4 v152, v[56:59], s[94:95] offset:512
	global_store_dwordx4 v152, v[48:51], s[94:95] offset:528
	s_mov_b64 exec, s[22:23]
	s_waitcnt lgkmcnt(2)
	s_and_saveexec_b64 s[22:23], s[16:17]
	v_pk_mul_f32 v[46:47], v[46:47], v[200:201] op_sel_hi:[1,0]
	v_pk_mul_f32 v[44:45], v[44:45], v[200:201] op_sel_hi:[1,0]
	v_pk_mul_f32 v[38:39], v[38:39], v[200:201] op_sel_hi:[1,0]
	v_pk_mul_f32 v[36:37], v[36:37], v[200:201] op_sel_hi:[1,0]
	v_pk_mul_f32 v[42:43], v[42:43], v[200:201] op_sel_hi:[1,0]
	v_pk_mul_f32 v[40:41], v[40:41], v[200:201] op_sel_hi:[1,0]
	v_pk_mul_f32 v[34:35], v[34:35], v[200:201] op_sel_hi:[1,0]
	v_pk_mul_f32 v[32:33], v[32:33], v[200:201] op_sel_hi:[1,0]
	v_lshlrev_b32_e32 v143, 12, v162
	v_lshl_add_u32 v152, v154, 2, v143
	v_pk_mul_f32 v[44:45], v[174:175], v[44:45]
	v_pk_mul_f32 v[46:47], v[176:177], v[46:47]
	v_pk_mul_f32 v[36:37], v[178:179], v[36:37]
	v_pk_mul_f32 v[38:39], v[180:181], v[38:39]
	v_pk_mul_f32 v[40:41], v[182:183], v[40:41]
	v_pk_mul_f32 v[42:43], v[184:185], v[42:43]
	v_pk_mul_f32 v[32:33], v[186:187], v[32:33]
	v_pk_mul_f32 v[34:35], v[188:189], v[34:35]
	global_store_dwordx4 v152, v[44:47], s[94:95]
	global_store_dwordx4 v152, v[36:39], s[94:95] offset:16
	global_store_dwordx4 v152, v[40:43], s[94:95] offset:512
	global_store_dwordx4 v152, v[32:35], s[94:95] offset:528
	s_mov_b64 exec, s[22:23]
	s_waitcnt lgkmcnt(1)
	s_and_saveexec_b64 s[22:23], s[18:19]
	v_pk_mul_f32 v[30:31], v[30:31], v[202:203] op_sel_hi:[1,0]
	v_pk_mul_f32 v[28:29], v[28:29], v[202:203] op_sel_hi:[1,0]
	v_pk_mul_f32 v[22:23], v[22:23], v[202:203] op_sel_hi:[1,0]
	v_pk_mul_f32 v[20:21], v[20:21], v[202:203] op_sel_hi:[1,0]
	v_pk_mul_f32 v[26:27], v[26:27], v[202:203] op_sel_hi:[1,0]
	v_pk_mul_f32 v[24:25], v[24:25], v[202:203] op_sel_hi:[1,0]
	v_pk_mul_f32 v[18:19], v[18:19], v[202:203] op_sel_hi:[1,0]
	v_pk_mul_f32 v[16:17], v[16:17], v[202:203] op_sel_hi:[1,0]
	v_lshlrev_b32_e32 v143, 12, v163
	v_lshl_add_u32 v152, v154, 2, v143
	v_pk_mul_f32 v[28:29], v[174:175], v[28:29]
	v_pk_mul_f32 v[30:31], v[176:177], v[30:31]
	v_pk_mul_f32 v[20:21], v[178:179], v[20:21]
	v_pk_mul_f32 v[22:23], v[180:181], v[22:23]
	v_pk_mul_f32 v[24:25], v[182:183], v[24:25]
	v_pk_mul_f32 v[26:27], v[184:185], v[26:27]
	v_pk_mul_f32 v[16:17], v[186:187], v[16:17]
	v_pk_mul_f32 v[18:19], v[188:189], v[18:19]
	global_store_dwordx4 v152, v[28:31], s[94:95]
	global_store_dwordx4 v152, v[20:23], s[94:95] offset:16
	global_store_dwordx4 v152, v[24:27], s[94:95] offset:512
	global_store_dwordx4 v152, v[16:19], s[94:95] offset:528
	s_mov_b64 exec, s[22:23]
	s_waitcnt lgkmcnt(0)
	s_and_saveexec_b64 s[22:23], s[20:21]
	v_pk_mul_f32 v[14:15], v[14:15], v[204:205] op_sel_hi:[1,0]
	v_pk_mul_f32 v[12:13], v[12:13], v[204:205] op_sel_hi:[1,0]
	v_pk_mul_f32 v[6:7], v[6:7], v[204:205] op_sel_hi:[1,0]
	v_pk_mul_f32 v[4:5], v[4:5], v[204:205] op_sel_hi:[1,0]
	v_pk_mul_f32 v[10:11], v[10:11], v[204:205] op_sel_hi:[1,0]
	v_pk_mul_f32 v[8:9], v[8:9], v[204:205] op_sel_hi:[1,0]
	v_pk_mul_f32 v[2:3], v[2:3], v[204:205] op_sel_hi:[1,0]
	v_pk_mul_f32 v[0:1], v[0:1], v[204:205] op_sel_hi:[1,0]
	v_lshlrev_b32_e32 v143, 12, v164
	v_lshl_add_u32 v152, v154, 2, v143
	v_pk_mul_f32 v[12:13], v[174:175], v[12:13]
	v_pk_mul_f32 v[14:15], v[176:177], v[14:15]
	v_pk_mul_f32 v[4:5], v[178:179], v[4:5]
	v_pk_mul_f32 v[6:7], v[180:181], v[6:7]
	v_pk_mul_f32 v[8:9], v[182:183], v[8:9]
	v_pk_mul_f32 v[10:11], v[184:185], v[10:11]
	v_pk_mul_f32 v[0:1], v[186:187], v[0:1]
	v_pk_mul_f32 v[2:3], v[188:189], v[2:3]
	global_store_dwordx4 v152, v[12:15], s[94:95]
	global_store_dwordx4 v152, v[4:7], s[94:95] offset:16
	global_store_dwordx4 v152, v[8:11], s[94:95] offset:512
	global_store_dwordx4 v152, v[0:3], s[94:95] offset:528
	s_mov_b64 exec, s[22:23]
	s_waitcnt lgkmcnt(0)
	s_barrier
	s_andn2_b64 vcc, exec, s[4:5]
	s_mov_b64 s[4:5], -1
	s_cbranch_vccnz .LBB0_1462
	s_and_b64 vcc, exec, s[0:1]
	s_cbranch_vccnz .LBB0_1461
	s_barrier
	s_branch .LBB0_1461
